# GEMM main loops: dropped the duplicated s_waitcnt lgkmcnt(0) that sat between s_setprio 1 and the first MFMA of 6 clusters per iteration (the identical wait two instructions earlier already covers it)
# speedup vs baseline: 1.0242x; 1.0036x over previous
.LBB0_227:
	s_add_u32 s22, s20, 0xfff80080
	s_addc_u32 s23, s21, -1
	s_add_i32 s59, 0, 0x10000
	ds_read_b128 v[140:143], v234
	ds_read_b128 v[144:147], v234 offset:1024
	ds_read_b128 v[148:151], v234 offset:2048
	ds_read_b128 v[170:173], v234 offset:3072
	s_cmp_eq_u32 s58, 28
	s_cselect_b32 s43, s5, s23
	s_cselect_b32 s42, s6, s22
	s_cselect_b32 s23, s7, s57
	s_cselect_b32 s22, s25, s35
	s_add_i32 m0, s49, 0xc000
	ds_read_b128 v[174:177], v168
	ds_read_b128 v[178:181], v168 offset:1024
	ds_read_b128 v[182:185], v168 offset:2048
	ds_read_b128 v[186:189], v168 offset:3072
	ds_read_b128 v[190:193], v168 offset:4096
	ds_read_b128 v[206:209], v168 offset:5120
	ds_read_b128 v[210:213], v168 offset:6144
	ds_read_b128 v[214:217], v168 offset:7168
	global_load_lds_dwordx4 v136, s[20:21]
	s_add_i32 m0, s49, 0xe000
	s_nop 0
	global_load_lds_dwordx4 v138, s[20:21]
	s_waitcnt lgkmcnt(8)
	s_barrier
	s_waitcnt lgkmcnt(0)
	s_setprio 1
	v_mfma_f32_16x16x32_bf16 v[124:127], v[140:143], v[174:177], v[124:127]
	v_mfma_f32_16x16x32_bf16 v[120:123], v[148:151], v[174:177], v[120:123]
	v_mfma_f32_16x16x32_bf16 v[108:111], v[140:143], v[182:185], v[108:111]
	v_mfma_f32_16x16x32_bf16 v[104:107], v[148:151], v[182:185], v[104:107]
	v_mfma_f32_16x16x32_bf16 v[92:95], v[140:143], v[190:193], v[92:95]
	v_mfma_f32_16x16x32_bf16 v[88:91], v[148:151], v[190:193], v[88:91]
	v_mfma_f32_16x16x32_bf16 v[76:79], v[140:143], v[210:213], v[76:79]
	v_mfma_f32_16x16x32_bf16 v[72:75], v[148:151], v[210:213], v[72:75]
	v_mfma_f32_16x16x32_bf16 v[124:127], v[144:147], v[178:181], v[124:127]
	v_mfma_f32_16x16x32_bf16 v[120:123], v[170:173], v[178:181], v[120:123]
	v_mfma_f32_16x16x32_bf16 v[108:111], v[144:147], v[186:189], v[108:111]
	v_mfma_f32_16x16x32_bf16 v[104:107], v[170:173], v[186:189], v[104:107]
	v_mfma_f32_16x16x32_bf16 v[92:95], v[144:147], v[206:209], v[92:95]
	v_mfma_f32_16x16x32_bf16 v[88:91], v[170:173], v[206:209], v[88:91]
	v_mfma_f32_16x16x32_bf16 v[76:79], v[144:147], v[214:217], v[76:79]
	v_mfma_f32_16x16x32_bf16 v[72:75], v[170:173], v[214:217], v[72:75]
	s_setprio 0
	s_barrier
	s_add_i32 s62, 0, 0x14000
	s_add_i32 s59, s59, s48
	s_mov_b32 m0, s59
	ds_read_b128 v[218:221], v235
	ds_read_b128 v[222:225], v235 offset:1024
	ds_read_b128 v[226:229], v235 offset:2048
	ds_read_b128 v[230:233], v235 offset:3072
	global_load_lds_dwordx4 v130, s[22:23]
	s_add_i32 m0, s59, 0x2000
	s_nop 0
	global_load_lds_dwordx4 v134, s[22:23]
	s_barrier
	s_waitcnt lgkmcnt(0)
	s_setprio 1
	v_mfma_f32_16x16x32_bf16 v[116:119], v[218:221], v[174:177], v[116:119]
	v_mfma_f32_16x16x32_bf16 v[112:115], v[226:229], v[174:177], v[112:115]
	v_mfma_f32_16x16x32_bf16 v[100:103], v[218:221], v[182:185], v[100:103]
	v_mfma_f32_16x16x32_bf16 v[96:99], v[226:229], v[182:185], v[96:99]
	v_mfma_f32_16x16x32_bf16 v[84:87], v[218:221], v[190:193], v[84:87]
	v_mfma_f32_16x16x32_bf16 v[80:83], v[226:229], v[190:193], v[80:83]
	v_mfma_f32_16x16x32_bf16 v[68:71], v[218:221], v[210:213], v[68:71]
	v_mfma_f32_16x16x32_bf16 v[64:67], v[226:229], v[210:213], v[64:67]
	v_mfma_f32_16x16x32_bf16 v[116:119], v[222:225], v[178:181], v[116:119]
	v_mfma_f32_16x16x32_bf16 v[112:115], v[230:233], v[178:181], v[112:115]
	v_mfma_f32_16x16x32_bf16 v[100:103], v[222:225], v[186:189], v[100:103]
	v_mfma_f32_16x16x32_bf16 v[96:99], v[230:233], v[186:189], v[96:99]
	v_mfma_f32_16x16x32_bf16 v[84:87], v[222:225], v[206:209], v[84:87]
	v_mfma_f32_16x16x32_bf16 v[80:83], v[230:233], v[206:209], v[80:83]
	v_mfma_f32_16x16x32_bf16 v[68:71], v[222:225], v[214:217], v[68:71]
	v_mfma_f32_16x16x32_bf16 v[64:67], v[230:233], v[214:217], v[64:67]
	s_setprio 0
	s_mov_b32 m0, s49
	s_add_u32 s98, s42, 0x80
	s_addc_u32 s99, s43, 0
	s_barrier
	ds_read_b128 v[174:177], v168 offset:16384
	ds_read_b128 v[178:181], v168 offset:17408
	ds_read_b128 v[182:185], v168 offset:18432
	ds_read_b128 v[186:189], v168 offset:19456
	ds_read_b128 v[190:193], v168 offset:20480
	ds_read_b128 v[206:209], v168 offset:21504
	ds_read_b128 v[210:213], v168 offset:22528
	ds_read_b128 v[214:217], v168 offset:23552
	global_load_lds_dwordx4 v128, s[42:43]
	s_mov_b32 m0, s50
	s_nop 0
	global_load_lds_dwordx4 v132, s[42:43]
	s_barrier
	s_waitcnt lgkmcnt(0)
	s_setprio 1
	v_mfma_f32_16x16x32_bf16 v[60:63], v[140:143], v[174:177], v[60:63]
	v_mfma_f32_16x16x32_bf16 v[56:59], v[148:151], v[174:177], v[56:59]
	v_mfma_f32_16x16x32_bf16 v[48:51], v[140:143], v[182:185], v[48:51]
	v_mfma_f32_16x16x32_bf16 v[40:43], v[148:151], v[182:185], v[40:43]
	v_mfma_f32_16x16x32_bf16 v[32:35], v[140:143], v[190:193], v[32:35]
	v_mfma_f32_16x16x32_bf16 v[24:27], v[148:151], v[190:193], v[24:27]
	v_mfma_f32_16x16x32_bf16 v[16:19], v[140:143], v[210:213], v[16:19]
	v_mfma_f32_16x16x32_bf16 v[8:11], v[148:151], v[210:213], v[8:11]
	v_mfma_f32_16x16x32_bf16 v[60:63], v[144:147], v[178:181], v[60:63]
	v_mfma_f32_16x16x32_bf16 v[56:59], v[170:173], v[178:181], v[56:59]
	v_mfma_f32_16x16x32_bf16 v[48:51], v[144:147], v[186:189], v[48:51]
	v_mfma_f32_16x16x32_bf16 v[40:43], v[170:173], v[186:189], v[40:43]
	v_mfma_f32_16x16x32_bf16 v[32:35], v[144:147], v[206:209], v[32:35]
	v_mfma_f32_16x16x32_bf16 v[24:27], v[170:173], v[206:209], v[24:27]
	v_mfma_f32_16x16x32_bf16 v[16:19], v[144:147], v[214:217], v[16:19]
	v_mfma_f32_16x16x32_bf16 v[8:11], v[170:173], v[214:217], v[8:11]
	s_setprio 0
	s_barrier
	s_add_u32 s60, s22, 0x80000
	s_addc_u32 s61, s23, 0
	s_add_i32 s59, s62, s48
	s_mov_b32 m0, s59
	s_nop 0
	global_load_lds_dwordx4 v130, s[60:61]
	s_add_i32 m0, s59, 0x2000
	s_nop 0
	global_load_lds_dwordx4 v134, s[60:61]
	s_waitcnt vmcnt(6)
	s_barrier
	s_setprio 1
	v_mfma_f32_16x16x32_bf16 v[52:55], v[218:221], v[174:177], v[52:55]
	v_mfma_f32_16x16x32_bf16 v[44:47], v[226:229], v[174:177], v[44:47]
	v_mfma_f32_16x16x32_bf16 v[36:39], v[218:221], v[182:185], v[36:39]
	v_mfma_f32_16x16x32_bf16 v[28:31], v[226:229], v[182:185], v[28:31]
	v_mfma_f32_16x16x32_bf16 v[20:23], v[218:221], v[190:193], v[20:23]
	v_mfma_f32_16x16x32_bf16 v[12:15], v[226:229], v[190:193], v[12:15]
	v_mfma_f32_16x16x32_bf16 v[4:7], v[218:221], v[210:213], v[4:7]
	v_mfma_f32_16x16x32_bf16 v[0:3], v[226:229], v[210:213], v[0:3]
	v_mfma_f32_16x16x32_bf16 v[52:55], v[222:225], v[178:181], v[52:55]
	v_mfma_f32_16x16x32_bf16 v[44:47], v[230:233], v[178:181], v[44:47]
	v_mfma_f32_16x16x32_bf16 v[36:39], v[222:225], v[186:189], v[36:39]
	v_mfma_f32_16x16x32_bf16 v[28:31], v[230:233], v[186:189], v[28:31]
	v_mfma_f32_16x16x32_bf16 v[20:23], v[222:225], v[206:209], v[20:23]
	v_mfma_f32_16x16x32_bf16 v[12:15], v[230:233], v[206:209], v[12:15]
	v_mfma_f32_16x16x32_bf16 v[4:7], v[222:225], v[214:217], v[4:7]
	v_mfma_f32_16x16x32_bf16 v[0:3], v[230:233], v[214:217], v[0:3]
	s_setprio 0
	s_add_i32 s59, 0, 0x18000
	s_barrier
	ds_read_b128 v[140:143], v236
	ds_read_b128 v[144:147], v236 offset:1024
	ds_read_b128 v[148:151], v236 offset:2048
	ds_read_b128 v[170:173], v236 offset:3072
	s_add_u32 s42, s42, 0x80000
	s_addc_u32 s43, s43, 0
	s_mov_b32 m0, s51
	ds_read_b128 v[174:177], v168 offset:32768
	ds_read_b128 v[178:181], v168 offset:33792
	ds_read_b128 v[182:185], v168 offset:34816
	ds_read_b128 v[186:189], v168 offset:35840
	ds_read_b128 v[190:193], v168 offset:36864
	ds_read_b128 v[206:209], v168 offset:37888
	ds_read_b128 v[210:213], v168 offset:38912
	ds_read_b128 v[214:217], v168 offset:39936
	global_load_lds_dwordx4 v128, s[42:43]
	s_mov_b32 m0, s52
	s_nop 0
	global_load_lds_dwordx4 v132, s[42:43]
	s_waitcnt lgkmcnt(8)
	s_barrier
	s_waitcnt lgkmcnt(0)
	s_setprio 1
	v_mfma_f32_16x16x32_bf16 v[124:127], v[140:143], v[174:177], v[124:127]
	v_mfma_f32_16x16x32_bf16 v[120:123], v[148:151], v[174:177], v[120:123]
	v_mfma_f32_16x16x32_bf16 v[108:111], v[140:143], v[182:185], v[108:111]
	v_mfma_f32_16x16x32_bf16 v[104:107], v[148:151], v[182:185], v[104:107]
	v_mfma_f32_16x16x32_bf16 v[92:95], v[140:143], v[190:193], v[92:95]
	v_mfma_f32_16x16x32_bf16 v[88:91], v[148:151], v[190:193], v[88:91]
	v_mfma_f32_16x16x32_bf16 v[76:79], v[140:143], v[210:213], v[76:79]
	v_mfma_f32_16x16x32_bf16 v[72:75], v[148:151], v[210:213], v[72:75]
	v_mfma_f32_16x16x32_bf16 v[124:127], v[144:147], v[178:181], v[124:127]
	v_mfma_f32_16x16x32_bf16 v[120:123], v[170:173], v[178:181], v[120:123]
	v_mfma_f32_16x16x32_bf16 v[108:111], v[144:147], v[186:189], v[108:111]
	v_mfma_f32_16x16x32_bf16 v[104:107], v[170:173], v[186:189], v[104:107]
	v_mfma_f32_16x16x32_bf16 v[92:95], v[144:147], v[206:209], v[92:95]
	v_mfma_f32_16x16x32_bf16 v[88:91], v[170:173], v[206:209], v[88:91]
	v_mfma_f32_16x16x32_bf16 v[76:79], v[144:147], v[214:217], v[76:79]
	v_mfma_f32_16x16x32_bf16 v[72:75], v[170:173], v[214:217], v[72:75]
	s_setprio 0
	s_barrier
	s_add_i32 s42, 0, 0x1c000
	s_add_i32 s43, s59, s48
	s_add_u32 s100, s22, 0x80
	s_addc_u32 s101, s23, 0
	s_mov_b32 m0, s43
	ds_read_b128 v[218:221], v237
	ds_read_b128 v[222:225], v237 offset:1024
	ds_read_b128 v[226:229], v237 offset:2048
	ds_read_b128 v[230:233], v237 offset:3072
	global_load_lds_dwordx4 v130, s[100:101]
	s_add_i32 m0, s43, 0x2000
	s_nop 0
	global_load_lds_dwordx4 v134, s[100:101]
	s_barrier
	s_waitcnt lgkmcnt(0)
	s_setprio 1
	v_mfma_f32_16x16x32_bf16 v[116:119], v[218:221], v[174:177], v[116:119]
	v_mfma_f32_16x16x32_bf16 v[112:115], v[226:229], v[174:177], v[112:115]
	v_mfma_f32_16x16x32_bf16 v[100:103], v[218:221], v[182:185], v[100:103]
	v_mfma_f32_16x16x32_bf16 v[96:99], v[226:229], v[182:185], v[96:99]
	v_mfma_f32_16x16x32_bf16 v[84:87], v[218:221], v[190:193], v[84:87]
	v_mfma_f32_16x16x32_bf16 v[80:83], v[226:229], v[190:193], v[80:83]
	v_mfma_f32_16x16x32_bf16 v[68:71], v[218:221], v[210:213], v[68:71]
	v_mfma_f32_16x16x32_bf16 v[64:67], v[226:229], v[210:213], v[64:67]
	v_mfma_f32_16x16x32_bf16 v[116:119], v[222:225], v[178:181], v[116:119]
	v_mfma_f32_16x16x32_bf16 v[112:115], v[230:233], v[178:181], v[112:115]
	v_mfma_f32_16x16x32_bf16 v[100:103], v[222:225], v[186:189], v[100:103]
	v_mfma_f32_16x16x32_bf16 v[96:99], v[230:233], v[186:189], v[96:99]
	v_mfma_f32_16x16x32_bf16 v[84:87], v[222:225], v[206:209], v[84:87]
	v_mfma_f32_16x16x32_bf16 v[80:83], v[230:233], v[206:209], v[80:83]
	v_mfma_f32_16x16x32_bf16 v[68:71], v[222:225], v[214:217], v[68:71]
	v_mfma_f32_16x16x32_bf16 v[64:67], v[230:233], v[214:217], v[64:67]
	s_setprio 0
	s_mov_b32 m0, s53
	s_barrier
	ds_read_b128 v[174:177], v168 offset:49152
	ds_read_b128 v[178:181], v168 offset:50176
	ds_read_b128 v[182:185], v168 offset:51200
	ds_read_b128 v[186:189], v168 offset:52224
	ds_read_b128 v[190:193], v168 offset:53248
	ds_read_b128 v[206:209], v168 offset:54272
	ds_read_b128 v[210:213], v168 offset:55296
	ds_read_b128 v[214:217], v168 offset:56320
	global_load_lds_dwordx4 v128, s[98:99]
	s_mov_b32 m0, s54
	s_nop 0
	global_load_lds_dwordx4 v132, s[98:99]
	s_barrier
	s_waitcnt lgkmcnt(0)
	s_setprio 1
	v_mfma_f32_16x16x32_bf16 v[60:63], v[140:143], v[174:177], v[60:63]
	v_mfma_f32_16x16x32_bf16 v[56:59], v[148:151], v[174:177], v[56:59]
	v_mfma_f32_16x16x32_bf16 v[48:51], v[140:143], v[182:185], v[48:51]
	v_mfma_f32_16x16x32_bf16 v[40:43], v[148:151], v[182:185], v[40:43]
	v_mfma_f32_16x16x32_bf16 v[32:35], v[140:143], v[190:193], v[32:35]
	v_mfma_f32_16x16x32_bf16 v[24:27], v[148:151], v[190:193], v[24:27]
	v_mfma_f32_16x16x32_bf16 v[16:19], v[140:143], v[210:213], v[16:19]
	v_mfma_f32_16x16x32_bf16 v[8:11], v[148:151], v[210:213], v[8:11]
	v_mfma_f32_16x16x32_bf16 v[60:63], v[144:147], v[178:181], v[60:63]
	v_mfma_f32_16x16x32_bf16 v[56:59], v[170:173], v[178:181], v[56:59]
	v_mfma_f32_16x16x32_bf16 v[48:51], v[144:147], v[186:189], v[48:51]
	v_mfma_f32_16x16x32_bf16 v[40:43], v[170:173], v[186:189], v[40:43]
	v_mfma_f32_16x16x32_bf16 v[32:35], v[144:147], v[206:209], v[32:35]
	v_mfma_f32_16x16x32_bf16 v[24:27], v[170:173], v[206:209], v[24:27]
	v_mfma_f32_16x16x32_bf16 v[16:19], v[144:147], v[214:217], v[16:19]
	v_mfma_f32_16x16x32_bf16 v[8:11], v[170:173], v[214:217], v[8:11]
	s_setprio 0
	s_barrier
	s_add_u32 s22, s22, 0x80080
	s_addc_u32 s23, s23, 0
	s_add_i32 s42, s42, s48
	s_mov_b32 m0, s42
	s_nop 0
	global_load_lds_dwordx4 v130, s[22:23]
	s_add_i32 m0, s42, 0x2000
	s_nop 0
	global_load_lds_dwordx4 v134, s[22:23]
	s_waitcnt vmcnt(6)
	s_barrier
	s_setprio 1
	v_mfma_f32_16x16x32_bf16 v[52:55], v[218:221], v[174:177], v[52:55]
	v_mfma_f32_16x16x32_bf16 v[44:47], v[226:229], v[174:177], v[44:47]
	v_mfma_f32_16x16x32_bf16 v[36:39], v[218:221], v[182:185], v[36:39]
	v_mfma_f32_16x16x32_bf16 v[28:31], v[226:229], v[182:185], v[28:31]
	v_mfma_f32_16x16x32_bf16 v[20:23], v[218:221], v[190:193], v[20:23]
	v_mfma_f32_16x16x32_bf16 v[12:15], v[226:229], v[190:193], v[12:15]
	v_mfma_f32_16x16x32_bf16 v[4:7], v[218:221], v[210:213], v[4:7]
	v_mfma_f32_16x16x32_bf16 v[0:3], v[226:229], v[210:213], v[0:3]
	v_mfma_f32_16x16x32_bf16 v[52:55], v[222:225], v[178:181], v[52:55]
	v_mfma_f32_16x16x32_bf16 v[44:47], v[230:233], v[178:181], v[44:47]
	v_mfma_f32_16x16x32_bf16 v[36:39], v[222:225], v[186:189], v[36:39]
	v_mfma_f32_16x16x32_bf16 v[28:31], v[230:233], v[186:189], v[28:31]
	v_mfma_f32_16x16x32_bf16 v[20:23], v[222:225], v[206:209], v[20:23]
	v_mfma_f32_16x16x32_bf16 v[12:15], v[230:233], v[206:209], v[12:15]
	v_mfma_f32_16x16x32_bf16 v[4:7], v[222:225], v[214:217], v[4:7]
	v_mfma_f32_16x16x32_bf16 v[0:3], v[230:233], v[214:217], v[0:3]
	s_setprio 0
	s_add_i32 s58, s58, 2
	s_add_u32 s20, s20, 0x100
	s_addc_u32 s21, s21, 0
	s_add_u32 s35, s35, 0x100
	s_addc_u32 s57, s57, 0
	s_cmp_gt_u32 s58, 29
	s_barrier
	s_cbranch_scc0 .LBB0_227
	v_lshl_add_u32 v140, s4, 8, v164
	s_cmp_gt_i32 s56, 23
	s_mov_b64 s[20:21], -1
	s_cbranch_scc1 .LBB0_262
	s_cmp_lt_i32 s56, 4
	s_cselect_b64 s[4:5], -1, 0
	s_and_b32 s6, s56, 0x7ffffffc
	s_cmp_eq_u32 s6, 16
	s_cselect_b64 s[6:7], -1, 0
	s_or_b64 s[20:21], s[4:5], s[6:7]
	s_and_b64 vcc, exec, s[20:21]
	v_mov_b32_e32 v149, v123
	v_mov_b32_e32 v148, v122
	v_mov_b32_e32 v163, v121
	v_mov_b32_e32 v162, v120
	v_mov_b32_e32 v147, v127
	v_mov_b32_e32 v146, v126
	v_mov_b32_e32 v151, v125
	v_mov_b32_e32 v150, v124
	s_cbranch_vccz .LBB0_231
	v_mul_f32_e32 v141, 0xbfb8aa3b, v124
	v_exp_f32_e32 v141, v141
	v_mul_f32_e32 v142, 0xbfb8aa3b, v120
	v_mul_f32_e32 v145, 0xbfb8aa3b, v126
	v_mul_f32_e32 v143, 0xbfb8aa3b, v125
	v_exp_f32_e32 v144, v142
	v_exp_f32_e32 v145, v145
	v_mul_f32_e32 v146, 0xbfb8aa3b, v122
	v_exp_f32_e32 v143, v143
	v_exp_f32_e32 v147, v146
	v_add_f32_e32 v141, 1.0, v141
	v_rcp_f32_e32 v142, v141
	v_add_f32_e32 v141, 1.0, v144
	v_add_f32_e32 v145, 1.0, v145
	v_rcp_f32_e32 v144, v141
	v_add_f32_e32 v141, 1.0, v143
	v_rcp_f32_e32 v146, v145
	v_add_f32_e32 v145, 1.0, v147
	v_mul_f32_e32 v147, 0xbfb8aa3b, v127
	v_rcp_f32_e32 v143, v141
	v_mul_f32_e32 v141, 0xbfb8aa3b, v121
	v_exp_f32_e32 v147, v147
	v_mul_f32_e32 v148, 0xbfb8aa3b, v123
	v_exp_f32_e32 v141, v141
	v_exp_f32_e32 v149, v148
	v_rcp_f32_e32 v148, v145
	v_add_f32_e32 v145, 1.0, v147
	v_add_f32_e32 v141, 1.0, v141
	v_rcp_f32_e32 v147, v145
	v_add_f32_e32 v145, 1.0, v149
	v_rcp_f32_e32 v149, v145
	v_rcp_f32_e32 v145, v141
	v_pk_mul_f32 v[146:147], v[126:127], v[146:147]
	v_pk_mul_f32 v[150:151], v[124:125], v[142:143]
	v_pk_mul_f32 v[148:149], v[122:123], v[148:149]
	v_pk_mul_f32 v[162:163], v[120:121], v[144:145]

.LBB0_561:
	s_add_u32 s38, s22, 0xfff80080
	s_addc_u32 s39, s23, -1
	s_add_i32 s84, 0, 0x10000
	ds_read_b128 v[72:75], v246
	ds_read_b128 v[76:79], v246 offset:1024
	ds_read_b128 v[84:87], v246 offset:2048
	ds_read_b128 v[92:95], v246 offset:3072
	s_cmp_eq_u32 s30, 28
	s_cselect_b32 s53, s5, s39
	s_cselect_b32 s52, s6, s38
	s_cselect_b32 s39, s1, s21
	s_cselect_b32 s38, s7, s17
	s_add_i32 m0, s61, 0xc000
	ds_read_b128 v[144:147], v208
	ds_read_b128 v[148:151], v208 offset:1024
	ds_read_b128 v[188:191], v208 offset:2048
	ds_read_b128 v[210:213], v208 offset:3072
	ds_read_b128 v[214:217], v208 offset:4096
	ds_read_b128 v[218:221], v208 offset:5120
	ds_read_b128 v[222:225], v208 offset:6144
	ds_read_b128 v[226:229], v208 offset:7168
	global_load_lds_dwordx4 v184, s[22:23]
	s_add_i32 m0, s61, 0xe000
	s_nop 0
	global_load_lds_dwordx4 v186, s[22:23]
	s_waitcnt lgkmcnt(8)
	s_barrier
	s_waitcnt lgkmcnt(0)
	s_setprio 1
	v_mfma_f32_16x16x32_bf16 v[140:143], v[72:75], v[144:147], v[140:143]
	v_mfma_f32_16x16x32_bf16 v[136:139], v[84:87], v[144:147], v[136:139]
	v_mfma_f32_16x16x32_bf16 v[124:127], v[72:75], v[188:191], v[124:127]
	v_mfma_f32_16x16x32_bf16 v[120:123], v[84:87], v[188:191], v[120:123]
	v_mfma_f32_16x16x32_bf16 v[108:111], v[72:75], v[214:217], v[108:111]
	v_mfma_f32_16x16x32_bf16 v[104:107], v[84:87], v[214:217], v[104:107]
	v_mfma_f32_16x16x32_bf16 v[88:91], v[72:75], v[222:225], v[88:91]
	v_mfma_f32_16x16x32_bf16 v[80:83], v[84:87], v[222:225], v[80:83]
	v_mfma_f32_16x16x32_bf16 v[140:143], v[76:79], v[148:151], v[140:143]
	v_mfma_f32_16x16x32_bf16 v[136:139], v[92:95], v[148:151], v[136:139]
	v_mfma_f32_16x16x32_bf16 v[124:127], v[76:79], v[210:213], v[124:127]
	v_mfma_f32_16x16x32_bf16 v[120:123], v[92:95], v[210:213], v[120:123]
	v_mfma_f32_16x16x32_bf16 v[108:111], v[76:79], v[218:221], v[108:111]
	v_mfma_f32_16x16x32_bf16 v[104:107], v[92:95], v[218:221], v[104:107]
	v_mfma_f32_16x16x32_bf16 v[88:91], v[76:79], v[226:229], v[88:91]
	v_mfma_f32_16x16x32_bf16 v[80:83], v[92:95], v[226:229], v[80:83]
	s_setprio 0
	s_barrier
	s_add_i32 s86, 0, 0x14000
	s_add_i32 s84, s84, s60
	ds_read_b128 v[230:233], v247
	ds_read_b128 v[234:237], v247 offset:1024
	ds_read_b128 v[238:241], v247 offset:2048
	ds_read_b128 v[242:245], v247 offset:3072
	s_mov_b32 m0, s84
	s_nop 0
	global_load_lds_dwordx4 v152, s[38:39]
	s_add_i32 m0, s84, 0x2000
	s_nop 0
	global_load_lds_dwordx4 v162, s[38:39]
	s_barrier
	s_waitcnt lgkmcnt(0)
	s_setprio 1
	v_mfma_f32_16x16x32_bf16 v[132:135], v[230:233], v[144:147], v[132:135]
	v_mfma_f32_16x16x32_bf16 v[128:131], v[238:241], v[144:147], v[128:131]
	v_mfma_f32_16x16x32_bf16 v[116:119], v[230:233], v[188:191], v[116:119]
	v_mfma_f32_16x16x32_bf16 v[112:115], v[238:241], v[188:191], v[112:115]
	v_mfma_f32_16x16x32_bf16 v[100:103], v[230:233], v[214:217], v[100:103]
	v_mfma_f32_16x16x32_bf16 v[96:99], v[238:241], v[214:217], v[96:99]
	v_mfma_f32_16x16x32_bf16 v[68:71], v[230:233], v[222:225], v[68:71]
	v_mfma_f32_16x16x32_bf16 v[64:67], v[238:241], v[222:225], v[64:67]
	v_mfma_f32_16x16x32_bf16 v[132:135], v[234:237], v[148:151], v[132:135]
	v_mfma_f32_16x16x32_bf16 v[128:131], v[242:245], v[148:151], v[128:131]
	v_mfma_f32_16x16x32_bf16 v[116:119], v[234:237], v[210:213], v[116:119]
	v_mfma_f32_16x16x32_bf16 v[112:115], v[242:245], v[210:213], v[112:115]
	v_mfma_f32_16x16x32_bf16 v[100:103], v[234:237], v[218:221], v[100:103]
	v_mfma_f32_16x16x32_bf16 v[96:99], v[242:245], v[218:221], v[96:99]
	v_mfma_f32_16x16x32_bf16 v[68:71], v[234:237], v[226:229], v[68:71]
	v_mfma_f32_16x16x32_bf16 v[64:67], v[242:245], v[226:229], v[64:67]
	s_setprio 0
	s_mov_b32 m0, s61
	s_add_u32 s98, s52, 0x80
	s_addc_u32 s99, s53, 0
	s_barrier
	ds_read_b128 v[144:147], v208 offset:16384
	ds_read_b128 v[148:151], v208 offset:17408
	ds_read_b128 v[188:191], v208 offset:18432
	ds_read_b128 v[210:213], v208 offset:19456
	ds_read_b128 v[214:217], v208 offset:20480
	ds_read_b128 v[218:221], v208 offset:21504
	ds_read_b128 v[222:225], v208 offset:22528
	ds_read_b128 v[226:229], v208 offset:23552
	global_load_lds_dwordx4 v166, s[52:53]
	s_mov_b32 m0, s62
	s_nop 0
	global_load_lds_dwordx4 v164, s[52:53]
	s_barrier
	s_waitcnt lgkmcnt(0)
	s_setprio 1
	v_mfma_f32_16x16x32_bf16 v[60:63], v[72:75], v[144:147], v[60:63]
	v_mfma_f32_16x16x32_bf16 v[56:59], v[84:87], v[144:147], v[56:59]
	v_mfma_f32_16x16x32_bf16 v[44:47], v[72:75], v[188:191], v[44:47]
	v_mfma_f32_16x16x32_bf16 v[40:43], v[84:87], v[188:191], v[40:43]
	v_mfma_f32_16x16x32_bf16 v[28:31], v[72:75], v[214:217], v[28:31]
	v_mfma_f32_16x16x32_bf16 v[24:27], v[84:87], v[214:217], v[24:27]
	v_mfma_f32_16x16x32_bf16 v[12:15], v[72:75], v[222:225], v[12:15]
	v_mfma_f32_16x16x32_bf16 v[8:11], v[84:87], v[222:225], v[8:11]
	v_mfma_f32_16x16x32_bf16 v[60:63], v[76:79], v[148:151], v[60:63]
	v_mfma_f32_16x16x32_bf16 v[56:59], v[92:95], v[148:151], v[56:59]
	v_mfma_f32_16x16x32_bf16 v[44:47], v[76:79], v[210:213], v[44:47]
	v_mfma_f32_16x16x32_bf16 v[40:43], v[92:95], v[210:213], v[40:43]
	v_mfma_f32_16x16x32_bf16 v[28:31], v[76:79], v[218:221], v[28:31]
	v_mfma_f32_16x16x32_bf16 v[24:27], v[92:95], v[218:221], v[24:27]
	v_mfma_f32_16x16x32_bf16 v[12:15], v[76:79], v[226:229], v[12:15]
	v_mfma_f32_16x16x32_bf16 v[8:11], v[92:95], v[226:229], v[8:11]
	s_setprio 0
	s_barrier
	s_add_u32 s84, s38, 0x80000
	s_addc_u32 s85, s39, 0
	s_add_i32 s86, s86, s60
	s_mov_b32 m0, s86
	s_nop 0
	global_load_lds_dwordx4 v152, s[84:85]
	s_add_i32 m0, s86, 0x2000
	s_nop 0
	global_load_lds_dwordx4 v162, s[84:85]
	s_waitcnt vmcnt(6)
	s_barrier
	s_setprio 1
	v_mfma_f32_16x16x32_bf16 v[52:55], v[230:233], v[144:147], v[52:55]
	v_mfma_f32_16x16x32_bf16 v[48:51], v[238:241], v[144:147], v[48:51]
	v_mfma_f32_16x16x32_bf16 v[36:39], v[230:233], v[188:191], v[36:39]
	v_mfma_f32_16x16x32_bf16 v[32:35], v[238:241], v[188:191], v[32:35]
	v_mfma_f32_16x16x32_bf16 v[20:23], v[230:233], v[214:217], v[20:23]
	v_mfma_f32_16x16x32_bf16 v[16:19], v[238:241], v[214:217], v[16:19]
	v_mfma_f32_16x16x32_bf16 v[4:7], v[230:233], v[222:225], v[4:7]
	v_mfma_f32_16x16x32_bf16 v[0:3], v[238:241], v[222:225], v[0:3]
	v_mfma_f32_16x16x32_bf16 v[52:55], v[234:237], v[148:151], v[52:55]
	v_mfma_f32_16x16x32_bf16 v[48:51], v[242:245], v[148:151], v[48:51]
	v_mfma_f32_16x16x32_bf16 v[36:39], v[234:237], v[210:213], v[36:39]
	v_mfma_f32_16x16x32_bf16 v[32:35], v[242:245], v[210:213], v[32:35]
	v_mfma_f32_16x16x32_bf16 v[20:23], v[234:237], v[218:221], v[20:23]
	v_mfma_f32_16x16x32_bf16 v[16:19], v[242:245], v[218:221], v[16:19]
	v_mfma_f32_16x16x32_bf16 v[4:7], v[234:237], v[226:229], v[4:7]
	v_mfma_f32_16x16x32_bf16 v[0:3], v[242:245], v[226:229], v[0:3]
	s_setprio 0
	s_add_i32 s84, 0, 0x18000
	s_barrier
	ds_read_b128 v[72:75], v248
	ds_read_b128 v[76:79], v248 offset:1024
	ds_read_b128 v[84:87], v248 offset:2048
	ds_read_b128 v[92:95], v248 offset:3072
	s_add_u32 s52, s52, 0x80000
	s_addc_u32 s53, s53, 0
	s_mov_b32 m0, s63
	ds_read_b128 v[144:147], v208 offset:32768
	ds_read_b128 v[148:151], v208 offset:33792
	ds_read_b128 v[188:191], v208 offset:34816
	ds_read_b128 v[210:213], v208 offset:35840
	ds_read_b128 v[214:217], v208 offset:36864
	ds_read_b128 v[218:221], v208 offset:37888
	ds_read_b128 v[222:225], v208 offset:38912
	ds_read_b128 v[226:229], v208 offset:39936
	global_load_lds_dwordx4 v166, s[52:53]
	s_mov_b32 m0, s68
	s_nop 0
	global_load_lds_dwordx4 v164, s[52:53]
	s_waitcnt lgkmcnt(8)
	s_barrier
	s_waitcnt lgkmcnt(0)
	s_setprio 1
	v_mfma_f32_16x16x32_bf16 v[140:143], v[72:75], v[144:147], v[140:143]
	v_mfma_f32_16x16x32_bf16 v[136:139], v[84:87], v[144:147], v[136:139]
	v_mfma_f32_16x16x32_bf16 v[124:127], v[72:75], v[188:191], v[124:127]
	v_mfma_f32_16x16x32_bf16 v[120:123], v[84:87], v[188:191], v[120:123]
	v_mfma_f32_16x16x32_bf16 v[108:111], v[72:75], v[214:217], v[108:111]
	v_mfma_f32_16x16x32_bf16 v[104:107], v[84:87], v[214:217], v[104:107]
	v_mfma_f32_16x16x32_bf16 v[88:91], v[72:75], v[222:225], v[88:91]
	v_mfma_f32_16x16x32_bf16 v[80:83], v[84:87], v[222:225], v[80:83]
	v_mfma_f32_16x16x32_bf16 v[140:143], v[76:79], v[148:151], v[140:143]
	v_mfma_f32_16x16x32_bf16 v[136:139], v[92:95], v[148:151], v[136:139]
	v_mfma_f32_16x16x32_bf16 v[124:127], v[76:79], v[210:213], v[124:127]
	v_mfma_f32_16x16x32_bf16 v[120:123], v[92:95], v[210:213], v[120:123]
	v_mfma_f32_16x16x32_bf16 v[108:111], v[76:79], v[218:221], v[108:111]
	v_mfma_f32_16x16x32_bf16 v[104:107], v[92:95], v[218:221], v[104:107]
	v_mfma_f32_16x16x32_bf16 v[88:91], v[76:79], v[226:229], v[88:91]
	v_mfma_f32_16x16x32_bf16 v[80:83], v[92:95], v[226:229], v[80:83]
	s_setprio 0
	s_barrier
	s_add_i32 s52, 0, 0x1c000
	s_add_i32 s53, s84, s60
	s_add_u32 s100, s38, 0x80
	s_addc_u32 s101, s39, 0
	s_mov_b32 m0, s53
	ds_read_b128 v[230:233], v249
	ds_read_b128 v[234:237], v249 offset:1024
	ds_read_b128 v[238:241], v249 offset:2048
	ds_read_b128 v[242:245], v249 offset:3072
	global_load_lds_dwordx4 v152, s[100:101]
	s_add_i32 m0, s53, 0x2000
	s_nop 0
	global_load_lds_dwordx4 v162, s[100:101]
	s_barrier
	s_waitcnt lgkmcnt(0)
	s_setprio 1
	v_mfma_f32_16x16x32_bf16 v[132:135], v[230:233], v[144:147], v[132:135]
	v_mfma_f32_16x16x32_bf16 v[128:131], v[238:241], v[144:147], v[128:131]
	v_mfma_f32_16x16x32_bf16 v[116:119], v[230:233], v[188:191], v[116:119]
	v_mfma_f32_16x16x32_bf16 v[112:115], v[238:241], v[188:191], v[112:115]
	v_mfma_f32_16x16x32_bf16 v[100:103], v[230:233], v[214:217], v[100:103]
	v_mfma_f32_16x16x32_bf16 v[96:99], v[238:241], v[214:217], v[96:99]
	v_mfma_f32_16x16x32_bf16 v[68:71], v[230:233], v[222:225], v[68:71]
	v_mfma_f32_16x16x32_bf16 v[64:67], v[238:241], v[222:225], v[64:67]
	v_mfma_f32_16x16x32_bf16 v[132:135], v[234:237], v[148:151], v[132:135]
	v_mfma_f32_16x16x32_bf16 v[128:131], v[242:245], v[148:151], v[128:131]
	v_mfma_f32_16x16x32_bf16 v[116:119], v[234:237], v[210:213], v[116:119]
	v_mfma_f32_16x16x32_bf16 v[112:115], v[242:245], v[210:213], v[112:115]
	v_mfma_f32_16x16x32_bf16 v[100:103], v[234:237], v[218:221], v[100:103]
	v_mfma_f32_16x16x32_bf16 v[96:99], v[242:245], v[218:221], v[96:99]
	v_mfma_f32_16x16x32_bf16 v[68:71], v[234:237], v[226:229], v[68:71]
	v_mfma_f32_16x16x32_bf16 v[64:67], v[242:245], v[226:229], v[64:67]
	s_setprio 0
	s_mov_b32 m0, s81
	s_barrier
	ds_read_b128 v[144:147], v208 offset:49152
	ds_read_b128 v[148:151], v208 offset:50176
	ds_read_b128 v[188:191], v208 offset:51200
	ds_read_b128 v[210:213], v208 offset:52224
	ds_read_b128 v[214:217], v208 offset:53248
	ds_read_b128 v[218:221], v208 offset:54272
	ds_read_b128 v[222:225], v208 offset:55296
	ds_read_b128 v[226:229], v208 offset:56320
	global_load_lds_dwordx4 v166, s[98:99]
	s_mov_b32 m0, s82
	s_nop 0
	global_load_lds_dwordx4 v164, s[98:99]
	s_barrier
	s_waitcnt lgkmcnt(0)
	s_setprio 1
	v_mfma_f32_16x16x32_bf16 v[60:63], v[72:75], v[144:147], v[60:63]
	v_mfma_f32_16x16x32_bf16 v[56:59], v[84:87], v[144:147], v[56:59]
	v_mfma_f32_16x16x32_bf16 v[44:47], v[72:75], v[188:191], v[44:47]
	v_mfma_f32_16x16x32_bf16 v[40:43], v[84:87], v[188:191], v[40:43]
	v_mfma_f32_16x16x32_bf16 v[28:31], v[72:75], v[214:217], v[28:31]
	v_mfma_f32_16x16x32_bf16 v[24:27], v[84:87], v[214:217], v[24:27]
	v_mfma_f32_16x16x32_bf16 v[12:15], v[72:75], v[222:225], v[12:15]
	v_mfma_f32_16x16x32_bf16 v[8:11], v[84:87], v[222:225], v[8:11]
	v_mfma_f32_16x16x32_bf16 v[60:63], v[76:79], v[148:151], v[60:63]
	v_mfma_f32_16x16x32_bf16 v[56:59], v[92:95], v[148:151], v[56:59]
	v_mfma_f32_16x16x32_bf16 v[44:47], v[76:79], v[210:213], v[44:47]
	v_mfma_f32_16x16x32_bf16 v[40:43], v[92:95], v[210:213], v[40:43]
	v_mfma_f32_16x16x32_bf16 v[28:31], v[76:79], v[218:221], v[28:31]
	v_mfma_f32_16x16x32_bf16 v[24:27], v[92:95], v[218:221], v[24:27]
	v_mfma_f32_16x16x32_bf16 v[12:15], v[76:79], v[226:229], v[12:15]
	v_mfma_f32_16x16x32_bf16 v[8:11], v[92:95], v[226:229], v[8:11]
	s_setprio 0
	s_barrier
	s_add_u32 s38, s38, 0x80080
	s_addc_u32 s39, s39, 0
	s_add_i32 s52, s52, s60
	s_mov_b32 m0, s52
	s_nop 0
	global_load_lds_dwordx4 v152, s[38:39]
	s_add_i32 m0, s52, 0x2000
	s_nop 0
	global_load_lds_dwordx4 v162, s[38:39]
	s_waitcnt vmcnt(6)
	s_barrier
	s_setprio 1
	v_mfma_f32_16x16x32_bf16 v[52:55], v[230:233], v[144:147], v[52:55]
	v_mfma_f32_16x16x32_bf16 v[48:51], v[238:241], v[144:147], v[48:51]
	v_mfma_f32_16x16x32_bf16 v[36:39], v[230:233], v[188:191], v[36:39]
	v_mfma_f32_16x16x32_bf16 v[32:35], v[238:241], v[188:191], v[32:35]
	v_mfma_f32_16x16x32_bf16 v[20:23], v[230:233], v[214:217], v[20:23]
	v_mfma_f32_16x16x32_bf16 v[16:19], v[238:241], v[214:217], v[16:19]
	v_mfma_f32_16x16x32_bf16 v[4:7], v[230:233], v[222:225], v[4:7]
	v_mfma_f32_16x16x32_bf16 v[0:3], v[238:241], v[222:225], v[0:3]
	v_mfma_f32_16x16x32_bf16 v[52:55], v[234:237], v[148:151], v[52:55]
	v_mfma_f32_16x16x32_bf16 v[48:51], v[242:245], v[148:151], v[48:51]
	v_mfma_f32_16x16x32_bf16 v[36:39], v[234:237], v[210:213], v[36:39]
	v_mfma_f32_16x16x32_bf16 v[32:35], v[242:245], v[210:213], v[32:35]
	v_mfma_f32_16x16x32_bf16 v[20:23], v[234:237], v[218:221], v[20:23]
	v_mfma_f32_16x16x32_bf16 v[16:19], v[242:245], v[218:221], v[16:19]
	v_mfma_f32_16x16x32_bf16 v[4:7], v[234:237], v[226:229], v[4:7]
	v_mfma_f32_16x16x32_bf16 v[0:3], v[242:245], v[226:229], v[0:3]
	s_setprio 0
	s_add_i32 s30, s30, 2
	s_add_u32 s22, s22, 0x100
	s_addc_u32 s23, s23, 0
	s_add_u32 s17, s17, 0x100
	s_addc_u32 s21, s21, 0
	s_cmp_gt_u32 s30, 29
	s_barrier
	s_cbranch_scc0 .LBB0_561
	v_lshl_or_b32 v188, s4, 8, v207
	v_ashrrev_i32_e32 v189, 31, v188
	s_cmp_lt_i32 s20, 16
	s_cselect_b32 s6, s44, s46
	s_cselect_b32 s7, s45, s47
	s_cselect_b32 s1, 0, 16
	s_sub_i32 s4, s20, s1
	s_mov_b32 s5, 0
	s_lshl_b64 s[4:5], s[4:5], 21
	s_add_u32 s38, s6, s4
	s_addc_u32 s39, s7, s5
	s_cmp_lt_i32 s20, 32
	s_cselect_b32 s1, 0x3000, s73
	s_cmp_lt_i32 s20, 16
	s_cselect_b32 s1, 0, s1
	s_lshl_b32 s1, s1, 2
	s_add_u32 s6, s79, s1
	s_addc_u32 s7, s80, 0
	s_mov_b32 s4, s20
	s_mov_b32 s5, 0
	s_lshl_b64 s[4:5], s[4:5], 20
	s_add_u32 s52, s69, s4
	s_addc_u32 s53, s78, s5
	v_lshl_add_u64 v[190:191], v[188:189], 2, s[6:7]
	s_mov_b64 s[4:5], 0x28504000
	v_lshl_add_u64 v[190:191], v[190:191], 0, s[4:5]
	global_load_dwordx4 v[92:95], v[190:191], off
	global_load_dwordx4 v[84:87], v[190:191], off offset:16
	global_load_dwordx4 v[76:79], v[190:191], off offset:512
	global_load_dwordx4 v[72:75], v[190:191], off offset:528
	v_lshl_add_u64 v[144:145], v[188:189], 1, s[52:53]
	s_and_b64 vcc, exec, s[64:65]
	s_cbranch_vccz .Lwo_epi_f32
	v_lshl_add_u64 v[148:149], v[168:169], 1, v[144:145]
	global_load_dwordx4 v[210:213], v[148:149], off
	global_load_dwordx4 v[214:217], v[148:149], off offset:256
	v_lshl_add_u64 v[148:149], v[170:171], 1, v[144:145]
	global_load_dwordx4 v[218:221], v[148:149], off
	global_load_dwordx4 v[222:225], v[148:149], off offset:256
	v_lshl_add_u64 v[148:149], v[172:173], 1, v[144:145]
	global_load_dwordx4 v[226:229], v[148:149], off
	global_load_dwordx4 v[230:233], v[148:149], off offset:256
	v_lshl_add_u64 v[148:149], v[174:175], 1, v[144:145]
	global_load_dwordx4 v[234:237], v[148:149], off
	global_load_dwordx4 v[238:241], v[148:149], off offset:256
	v_lshl_add_u64 v[148:149], v[176:177], 1, v[144:145]
	global_load_dwordx4 v[242:245], v[148:149], off
	s_waitcnt vmcnt(8)
	v_lshlrev_b32_e32 v188, 16, v210
	v_and_b32_e32 v189, 0xffff0000, v210
	v_lshlrev_b32_e32 v190, 16, v211
	v_and_b32_e32 v191, 0xffff0000, v211
	v_lshlrev_b32_e32 v246, 16, v212
	v_and_b32_e32 v247, 0xffff0000, v212
	v_lshlrev_b32_e32 v248, 16, v213
	v_and_b32_e32 v249, 0xffff0000, v213
	global_load_dwordx4 v[210:213], v[148:149], off offset:256
	v_lshl_add_u64 v[150:151], v[168:169], 1, v[144:145]
	v_pk_fma_f32 v[140:141], v[140:141], v[92:93], v[188:189]
	v_pk_fma_f32 v[142:143], v[142:143], v[94:95], v[190:191]
	v_pk_fma_f32 v[136:137], v[136:137], v[84:85], v[246:247]
	v_pk_fma_f32 v[138:139], v[138:139], v[86:87], v[248:249]
	v_cvt_pk_bf16_f32 v140, v140, v141
	v_cvt_pk_bf16_f32 v141, v142, v143
	v_cvt_pk_bf16_f32 v142, v136, v137
	v_cvt_pk_bf16_f32 v143, v138, v139
	global_store_dwordx4 v[150:151], v[140:143], off
	s_waitcnt vmcnt(9)
	v_lshlrev_b32_e32 v188, 16, v214
	v_and_b32_e32 v189, 0xffff0000, v214
	v_lshlrev_b32_e32 v190, 16, v215
	v_and_b32_e32 v191, 0xffff0000, v215
	v_lshlrev_b32_e32 v246, 16, v216
	v_and_b32_e32 v247, 0xffff0000, v216
	v_lshlrev_b32_e32 v248, 16, v217
	v_and_b32_e32 v249, 0xffff0000, v217
	v_lshl_add_u64 v[148:149], v[178:179], 1, v[144:145]
	global_load_dwordx4 v[214:217], v[148:149], off
	v_pk_fma_f32 v[132:133], v[132:133], v[76:77], v[188:189]
	v_pk_fma_f32 v[134:135], v[134:135], v[78:79], v[190:191]
	v_pk_fma_f32 v[128:129], v[128:129], v[72:73], v[246:247]
	v_pk_fma_f32 v[130:131], v[130:131], v[74:75], v[248:249]
	v_cvt_pk_bf16_f32 v132, v132, v133
	v_cvt_pk_bf16_f32 v133, v134, v135
	v_cvt_pk_bf16_f32 v134, v128, v129
	v_cvt_pk_bf16_f32 v135, v130, v131
	global_store_dwordx4 v[150:151], v[132:135], off offset:256
	s_waitcnt vmcnt(10)
	v_lshlrev_b32_e32 v188, 16, v218
	v_and_b32_e32 v189, 0xffff0000, v218
	v_lshlrev_b32_e32 v190, 16, v219
	v_and_b32_e32 v191, 0xffff0000, v219
	v_lshlrev_b32_e32 v246, 16, v220
	v_and_b32_e32 v247, 0xffff0000, v220
	v_lshlrev_b32_e32 v248, 16, v221
	v_and_b32_e32 v249, 0xffff0000, v221
	global_load_dwordx4 v[218:221], v[148:149], off offset:256
	v_lshl_add_u64 v[192:193], v[170:171], 1, v[144:145]
	v_pk_fma_f32 v[124:125], v[124:125], v[92:93], v[188:189]
	v_pk_fma_f32 v[126:127], v[126:127], v[94:95], v[190:191]
	v_pk_fma_f32 v[120:121], v[120:121], v[84:85], v[246:247]
	v_pk_fma_f32 v[122:123], v[122:123], v[86:87], v[248:249]
	v_cvt_pk_bf16_f32 v124, v124, v125
	v_cvt_pk_bf16_f32 v125, v126, v127
	v_cvt_pk_bf16_f32 v126, v120, v121
	v_cvt_pk_bf16_f32 v127, v122, v123
	global_store_dwordx4 v[192:193], v[124:127], off
	s_waitcnt vmcnt(11)
	v_lshlrev_b32_e32 v188, 16, v222
	v_and_b32_e32 v189, 0xffff0000, v222
	v_lshlrev_b32_e32 v190, 16, v223
	v_and_b32_e32 v191, 0xffff0000, v223
	v_lshlrev_b32_e32 v246, 16, v224
	v_and_b32_e32 v247, 0xffff0000, v224
	v_lshlrev_b32_e32 v248, 16, v225
	v_and_b32_e32 v249, 0xffff0000, v225
	v_lshl_add_u64 v[148:149], v[180:181], 1, v[144:145]
	global_load_dwordx4 v[222:225], v[148:149], off
	v_pk_fma_f32 v[116:117], v[116:117], v[76:77], v[188:189]
	v_pk_fma_f32 v[118:119], v[118:119], v[78:79], v[190:191]
	v_pk_fma_f32 v[112:113], v[112:113], v[72:73], v[246:247]
	v_pk_fma_f32 v[114:115], v[114:115], v[74:75], v[248:249]
	v_cvt_pk_bf16_f32 v116, v116, v117
	v_cvt_pk_bf16_f32 v117, v118, v119
	v_cvt_pk_bf16_f32 v118, v112, v113
	v_cvt_pk_bf16_f32 v119, v114, v115
	global_store_dwordx4 v[192:193], v[116:119], off offset:256
	s_waitcnt vmcnt(12)
	v_lshlrev_b32_e32 v188, 16, v226
	v_and_b32_e32 v189, 0xffff0000, v226
	v_lshlrev_b32_e32 v190, 16, v227
	v_and_b32_e32 v191, 0xffff0000, v227
	v_lshlrev_b32_e32 v246, 16, v228
	v_and_b32_e32 v247, 0xffff0000, v228
	v_lshlrev_b32_e32 v248, 16, v229
	v_and_b32_e32 v249, 0xffff0000, v229
	global_load_dwordx4 v[226:229], v[148:149], off offset:256
	v_lshl_add_u64 v[150:151], v[172:173], 1, v[144:145]
	v_pk_fma_f32 v[108:109], v[108:109], v[92:93], v[188:189]
	v_pk_fma_f32 v[110:111], v[110:111], v[94:95], v[190:191]
	v_pk_fma_f32 v[104:105], v[104:105], v[84:85], v[246:247]
	v_pk_fma_f32 v[106:107], v[106:107], v[86:87], v[248:249]
	v_cvt_pk_bf16_f32 v108, v108, v109
	v_cvt_pk_bf16_f32 v109, v110, v111
	v_cvt_pk_bf16_f32 v110, v104, v105
	v_cvt_pk_bf16_f32 v111, v106, v107
	global_store_dwordx4 v[150:151], v[108:111], off
	s_waitcnt vmcnt(13)
	v_lshlrev_b32_e32 v188, 16, v230
	v_and_b32_e32 v189, 0xffff0000, v230
	v_lshlrev_b32_e32 v190, 16, v231
	v_and_b32_e32 v191, 0xffff0000, v231
	v_lshlrev_b32_e32 v246, 16, v232
	v_and_b32_e32 v247, 0xffff0000, v232
	v_lshlrev_b32_e32 v248, 16, v233
	v_and_b32_e32 v249, 0xffff0000, v233
	v_lshl_add_u64 v[148:149], v[182:183], 1, v[144:145]
	global_load_dwordx4 v[230:233], v[148:149], off
	v_pk_fma_f32 v[100:101], v[100:101], v[76:77], v[188:189]
	v_pk_fma_f32 v[102:103], v[102:103], v[78:79], v[190:191]
	v_pk_fma_f32 v[96:97], v[96:97], v[72:73], v[246:247]
	v_pk_fma_f32 v[98:99], v[98:99], v[74:75], v[248:249]
	v_cvt_pk_bf16_f32 v100, v100, v101
	v_cvt_pk_bf16_f32 v101, v102, v103
	v_cvt_pk_bf16_f32 v102, v96, v97
	v_cvt_pk_bf16_f32 v103, v98, v99
	global_store_dwordx4 v[150:151], v[100:103], off offset:256
	s_waitcnt vmcnt(14)
	v_lshlrev_b32_e32 v188, 16, v234
	v_and_b32_e32 v189, 0xffff0000, v234
	v_lshlrev_b32_e32 v190, 16, v235
	v_and_b32_e32 v191, 0xffff0000, v235
	v_lshlrev_b32_e32 v246, 16, v236
	v_and_b32_e32 v247, 0xffff0000, v236
	v_lshlrev_b32_e32 v248, 16, v237
	v_and_b32_e32 v249, 0xffff0000, v237
	global_load_dwordx4 v[234:237], v[148:149], off offset:256
	v_lshl_add_u64 v[192:193], v[174:175], 1, v[144:145]
	v_pk_fma_f32 v[88:89], v[88:89], v[92:93], v[188:189]
	v_pk_fma_f32 v[90:91], v[90:91], v[94:95], v[190:191]
	v_pk_fma_f32 v[80:81], v[80:81], v[84:85], v[246:247]
	v_pk_fma_f32 v[82:83], v[82:83], v[86:87], v[248:249]
	v_cvt_pk_bf16_f32 v88, v88, v89
	v_cvt_pk_bf16_f32 v89, v90, v91
	v_cvt_pk_bf16_f32 v90, v80, v81
	v_cvt_pk_bf16_f32 v91, v82, v83
	global_store_dwordx4 v[192:193], v[88:91], off
	s_waitcnt vmcnt(15)
	v_lshlrev_b32_e32 v188, 16, v238
	v_and_b32_e32 v189, 0xffff0000, v238
	v_lshlrev_b32_e32 v190, 16, v239
	v_and_b32_e32 v191, 0xffff0000, v239
	v_lshlrev_b32_e32 v246, 16, v240
	v_and_b32_e32 v247, 0xffff0000, v240
	v_lshlrev_b32_e32 v248, 16, v241
	v_and_b32_e32 v249, 0xffff0000, v241
	v_pk_fma_f32 v[68:69], v[68:69], v[76:77], v[188:189]
	v_pk_fma_f32 v[70:71], v[70:71], v[78:79], v[190:191]
	v_pk_fma_f32 v[64:65], v[64:65], v[72:73], v[246:247]
	v_pk_fma_f32 v[66:67], v[66:67], v[74:75], v[248:249]
	v_cvt_pk_bf16_f32 v68, v68, v69
	v_cvt_pk_bf16_f32 v69, v70, v71
	v_cvt_pk_bf16_f32 v70, v64, v65
	v_cvt_pk_bf16_f32 v71, v66, v67
	global_store_dwordx4 v[192:193], v[68:71], off offset:256
	s_waitcnt vmcnt(15)
	v_lshlrev_b32_e32 v188, 16, v242
	v_and_b32_e32 v189, 0xffff0000, v242
	v_lshlrev_b32_e32 v190, 16, v243
	v_and_b32_e32 v191, 0xffff0000, v243
	v_lshlrev_b32_e32 v246, 16, v244
	v_and_b32_e32 v247, 0xffff0000, v244
	v_lshlrev_b32_e32 v248, 16, v245
	v_and_b32_e32 v249, 0xffff0000, v245
	v_lshl_add_u64 v[150:151], v[176:177], 1, v[144:145]
	v_pk_fma_f32 v[60:61], v[60:61], v[92:93], v[188:189]
	v_pk_fma_f32 v[62:63], v[62:63], v[94:95], v[190:191]
	v_pk_fma_f32 v[56:57], v[56:57], v[84:85], v[246:247]
	v_pk_fma_f32 v[58:59], v[58:59], v[86:87], v[248:249]
	v_cvt_pk_bf16_f32 v60, v60, v61
	v_cvt_pk_bf16_f32 v61, v62, v63
	v_cvt_pk_bf16_f32 v62, v56, v57
	v_cvt_pk_bf16_f32 v63, v58, v59
	global_store_dwordx4 v[150:151], v[60:63], off
	s_waitcnt vmcnt(15)
	v_lshlrev_b32_e32 v188, 16, v210
	v_and_b32_e32 v189, 0xffff0000, v210
	v_lshlrev_b32_e32 v190, 16, v211
	v_and_b32_e32 v191, 0xffff0000, v211
	v_lshlrev_b32_e32 v246, 16, v212
	v_and_b32_e32 v247, 0xffff0000, v212
	v_lshlrev_b32_e32 v248, 16, v213
	v_and_b32_e32 v249, 0xffff0000, v213
	v_pk_fma_f32 v[52:53], v[52:53], v[76:77], v[188:189]
	v_pk_fma_f32 v[54:55], v[54:55], v[78:79], v[190:191]
	v_pk_fma_f32 v[48:49], v[48:49], v[72:73], v[246:247]
	v_pk_fma_f32 v[50:51], v[50:51], v[74:75], v[248:249]
	v_cvt_pk_bf16_f32 v52, v52, v53
	v_cvt_pk_bf16_f32 v53, v54, v55
	v_cvt_pk_bf16_f32 v54, v48, v49
	v_cvt_pk_bf16_f32 v55, v50, v51
	global_store_dwordx4 v[150:151], v[52:55], off offset:256
	s_waitcnt vmcnt(14)
	v_lshlrev_b32_e32 v188, 16, v214
	v_and_b32_e32 v189, 0xffff0000, v214
	v_lshlrev_b32_e32 v190, 16, v215
	v_and_b32_e32 v191, 0xffff0000, v215
	v_lshlrev_b32_e32 v246, 16, v216
	v_and_b32_e32 v247, 0xffff0000, v216
	v_lshlrev_b32_e32 v248, 16, v217
	v_and_b32_e32 v249, 0xffff0000, v217
	v_lshl_add_u64 v[192:193], v[178:179], 1, v[144:145]
	v_pk_fma_f32 v[44:45], v[44:45], v[92:93], v[188:189]
	v_pk_fma_f32 v[46:47], v[46:47], v[94:95], v[190:191]
	v_pk_fma_f32 v[40:41], v[40:41], v[84:85], v[246:247]
	v_pk_fma_f32 v[42:43], v[42:43], v[86:87], v[248:249]
	v_cvt_pk_bf16_f32 v44, v44, v45
	v_cvt_pk_bf16_f32 v45, v46, v47
	v_cvt_pk_bf16_f32 v46, v40, v41
	v_cvt_pk_bf16_f32 v47, v42, v43
	global_store_dwordx4 v[192:193], v[44:47], off
	s_waitcnt vmcnt(13)
	v_lshlrev_b32_e32 v188, 16, v218
	v_and_b32_e32 v189, 0xffff0000, v218
	v_lshlrev_b32_e32 v190, 16, v219
	v_and_b32_e32 v191, 0xffff0000, v219
	v_lshlrev_b32_e32 v246, 16, v220
	v_and_b32_e32 v247, 0xffff0000, v220
	v_lshlrev_b32_e32 v248, 16, v221
	v_and_b32_e32 v249, 0xffff0000, v221
	v_pk_fma_f32 v[36:37], v[36:37], v[76:77], v[188:189]
	v_pk_fma_f32 v[38:39], v[38:39], v[78:79], v[190:191]
	v_pk_fma_f32 v[32:33], v[32:33], v[72:73], v[246:247]
	v_pk_fma_f32 v[34:35], v[34:35], v[74:75], v[248:249]
	v_cvt_pk_bf16_f32 v36, v36, v37
	v_cvt_pk_bf16_f32 v37, v38, v39
	v_cvt_pk_bf16_f32 v38, v32, v33
	v_cvt_pk_bf16_f32 v39, v34, v35
	global_store_dwordx4 v[192:193], v[36:39], off offset:256
	s_waitcnt vmcnt(12)
	v_lshlrev_b32_e32 v188, 16, v222
	v_and_b32_e32 v189, 0xffff0000, v222
	v_lshlrev_b32_e32 v190, 16, v223
	v_and_b32_e32 v191, 0xffff0000, v223
	v_lshlrev_b32_e32 v246, 16, v224
	v_and_b32_e32 v247, 0xffff0000, v224
	v_lshlrev_b32_e32 v248, 16, v225
	v_and_b32_e32 v249, 0xffff0000, v225
	v_lshl_add_u64 v[150:151], v[180:181], 1, v[144:145]
	v_pk_fma_f32 v[28:29], v[28:29], v[92:93], v[188:189]
	v_pk_fma_f32 v[30:31], v[30:31], v[94:95], v[190:191]
	v_pk_fma_f32 v[24:25], v[24:25], v[84:85], v[246:247]
	v_pk_fma_f32 v[26:27], v[26:27], v[86:87], v[248:249]
	v_cvt_pk_bf16_f32 v28, v28, v29
	v_cvt_pk_bf16_f32 v29, v30, v31
	v_cvt_pk_bf16_f32 v30, v24, v25
	v_cvt_pk_bf16_f32 v31, v26, v27
	global_store_dwordx4 v[150:151], v[28:31], off
	s_waitcnt vmcnt(11)
	v_lshlrev_b32_e32 v188, 16, v226
	v_and_b32_e32 v189, 0xffff0000, v226
	v_lshlrev_b32_e32 v190, 16, v227
	v_and_b32_e32 v191, 0xffff0000, v227
	v_lshlrev_b32_e32 v246, 16, v228
	v_and_b32_e32 v247, 0xffff0000, v228
	v_lshlrev_b32_e32 v248, 16, v229
	v_and_b32_e32 v249, 0xffff0000, v229
	v_pk_fma_f32 v[20:21], v[20:21], v[76:77], v[188:189]
	v_pk_fma_f32 v[22:23], v[22:23], v[78:79], v[190:191]
	v_pk_fma_f32 v[16:17], v[16:17], v[72:73], v[246:247]
	v_pk_fma_f32 v[18:19], v[18:19], v[74:75], v[248:249]
	v_cvt_pk_bf16_f32 v20, v20, v21
	v_cvt_pk_bf16_f32 v21, v22, v23
	v_cvt_pk_bf16_f32 v22, v16, v17
	v_cvt_pk_bf16_f32 v23, v18, v19
	global_store_dwordx4 v[150:151], v[20:23], off offset:256
	s_waitcnt vmcnt(10)
	v_lshlrev_b32_e32 v188, 16, v230
	v_and_b32_e32 v189, 0xffff0000, v230
	v_lshlrev_b32_e32 v190, 16, v231
	v_and_b32_e32 v191, 0xffff0000, v231
	v_lshlrev_b32_e32 v246, 16, v232
	v_and_b32_e32 v247, 0xffff0000, v232
	v_lshlrev_b32_e32 v248, 16, v233
	v_and_b32_e32 v249, 0xffff0000, v233
	v_lshl_add_u64 v[192:193], v[182:183], 1, v[144:145]
	v_pk_fma_f32 v[12:13], v[12:13], v[92:93], v[188:189]
	v_pk_fma_f32 v[14:15], v[14:15], v[94:95], v[190:191]
	v_pk_fma_f32 v[8:9], v[8:9], v[84:85], v[246:247]
	v_pk_fma_f32 v[10:11], v[10:11], v[86:87], v[248:249]
	v_cvt_pk_bf16_f32 v12, v12, v13
	v_cvt_pk_bf16_f32 v13, v14, v15
	v_cvt_pk_bf16_f32 v14, v8, v9
	v_cvt_pk_bf16_f32 v15, v10, v11
	global_store_dwordx4 v[192:193], v[12:15], off
	s_waitcnt vmcnt(9)
	v_lshlrev_b32_e32 v188, 16, v234
	v_and_b32_e32 v189, 0xffff0000, v234
	v_lshlrev_b32_e32 v190, 16, v235
	v_and_b32_e32 v191, 0xffff0000, v235
	v_lshlrev_b32_e32 v246, 16, v236
	v_and_b32_e32 v247, 0xffff0000, v236
	v_lshlrev_b32_e32 v248, 16, v237
	v_and_b32_e32 v249, 0xffff0000, v237
	v_pk_fma_f32 v[4:5], v[4:5], v[76:77], v[188:189]
	v_pk_fma_f32 v[6:7], v[6:7], v[78:79], v[190:191]
	v_pk_fma_f32 v[0:1], v[0:1], v[72:73], v[246:247]
	v_pk_fma_f32 v[2:3], v[2:3], v[74:75], v[248:249]
	v_cvt_pk_bf16_f32 v4, v4, v5
	v_cvt_pk_bf16_f32 v5, v6, v7
	v_cvt_pk_bf16_f32 v6, v0, v1
	v_cvt_pk_bf16_f32 v7, v2, v3
	global_store_dwordx4 v[192:193], v[4:7], off offset:256
	s_branch .Lwo_epi_done

.LBB0_773:
	s_add_u32 s22, s20, 0xfff80080
	s_addc_u32 s23, s21, -1
	s_add_i32 s61, 0, 0x10000
	ds_read_b128 v[144:147], v230
	ds_read_b128 v[148:151], v230 offset:1024
	ds_read_b128 v[162:165], v230 offset:2048
	ds_read_b128 v[166:169], v230 offset:3072
	s_cmp_eq_u32 s60, 28
	s_cselect_b32 s47, s35, s23
	s_cselect_b32 s46, s56, s22
	s_cselect_b32 s23, s25, s59
	s_cselect_b32 s22, s57, s58
	s_add_i32 m0, s5, 0xc000
	ds_read_b128 v[170:173], v143
	ds_read_b128 v[174:177], v143 offset:1024
	ds_read_b128 v[178:181], v143 offset:2048
	ds_read_b128 v[182:185], v143 offset:3072
	ds_read_b128 v[186:189], v143 offset:4096
	ds_read_b128 v[190:193], v143 offset:5120
	ds_read_b128 v[206:209], v143 offset:6144
	ds_read_b128 v[210:213], v143 offset:7168
	global_load_lds_dwordx4 v134, s[20:21]
	s_add_i32 m0, s5, 0xe000
	s_nop 0
	global_load_lds_dwordx4 v136, s[20:21]
	s_waitcnt lgkmcnt(8)
	s_barrier
	s_waitcnt lgkmcnt(0)
	s_setprio 1
	v_mfma_f32_16x16x32_bf16 v[124:127], v[144:147], v[170:173], v[124:127]
	v_mfma_f32_16x16x32_bf16 v[120:123], v[162:165], v[170:173], v[120:123]
	v_mfma_f32_16x16x32_bf16 v[108:111], v[144:147], v[178:181], v[108:111]
	v_mfma_f32_16x16x32_bf16 v[104:107], v[162:165], v[178:181], v[104:107]
	v_mfma_f32_16x16x32_bf16 v[92:95], v[144:147], v[186:189], v[92:95]
	v_mfma_f32_16x16x32_bf16 v[88:91], v[162:165], v[186:189], v[88:91]
	v_mfma_f32_16x16x32_bf16 v[76:79], v[144:147], v[206:209], v[76:79]
	v_mfma_f32_16x16x32_bf16 v[72:75], v[162:165], v[206:209], v[72:75]
	v_mfma_f32_16x16x32_bf16 v[124:127], v[148:151], v[174:177], v[124:127]
	v_mfma_f32_16x16x32_bf16 v[120:123], v[166:169], v[174:177], v[120:123]
	v_mfma_f32_16x16x32_bf16 v[108:111], v[148:151], v[182:185], v[108:111]
	v_mfma_f32_16x16x32_bf16 v[104:107], v[166:169], v[182:185], v[104:107]
	v_mfma_f32_16x16x32_bf16 v[92:95], v[148:151], v[190:193], v[92:95]
	v_mfma_f32_16x16x32_bf16 v[88:91], v[166:169], v[190:193], v[88:91]
	v_mfma_f32_16x16x32_bf16 v[76:79], v[148:151], v[210:213], v[76:79]
	v_mfma_f32_16x16x32_bf16 v[72:75], v[166:169], v[210:213], v[72:75]
	s_setprio 0
	s_barrier
	s_add_i32 s68, 0, 0x14000
	s_add_i32 s61, s61, s4
	ds_read_b128 v[214:217], v231
	ds_read_b128 v[218:221], v231 offset:1024
	ds_read_b128 v[222:225], v231 offset:2048
	ds_read_b128 v[226:229], v231 offset:3072
	s_mov_b32 m0, s61
	s_nop 0
	global_load_lds_dwordx4 v152, s[22:23]
	s_add_i32 m0, s61, 0x2000
	s_nop 0
	global_load_lds_dwordx4 v132, s[22:23]
	s_barrier
	s_waitcnt lgkmcnt(0)
	s_setprio 1
	v_mfma_f32_16x16x32_bf16 v[116:119], v[214:217], v[170:173], v[116:119]
	v_mfma_f32_16x16x32_bf16 v[112:115], v[222:225], v[170:173], v[112:115]
	v_mfma_f32_16x16x32_bf16 v[100:103], v[214:217], v[178:181], v[100:103]
	v_mfma_f32_16x16x32_bf16 v[96:99], v[222:225], v[178:181], v[96:99]
	v_mfma_f32_16x16x32_bf16 v[84:87], v[214:217], v[186:189], v[84:87]
	v_mfma_f32_16x16x32_bf16 v[80:83], v[222:225], v[186:189], v[80:83]
	v_mfma_f32_16x16x32_bf16 v[68:71], v[214:217], v[206:209], v[68:71]
	v_mfma_f32_16x16x32_bf16 v[64:67], v[222:225], v[206:209], v[64:67]
	v_mfma_f32_16x16x32_bf16 v[116:119], v[218:221], v[174:177], v[116:119]
	v_mfma_f32_16x16x32_bf16 v[112:115], v[226:229], v[174:177], v[112:115]
	v_mfma_f32_16x16x32_bf16 v[100:103], v[218:221], v[182:185], v[100:103]
	v_mfma_f32_16x16x32_bf16 v[96:99], v[226:229], v[182:185], v[96:99]
	v_mfma_f32_16x16x32_bf16 v[84:87], v[218:221], v[190:193], v[84:87]
	v_mfma_f32_16x16x32_bf16 v[80:83], v[226:229], v[190:193], v[80:83]
	v_mfma_f32_16x16x32_bf16 v[68:71], v[218:221], v[210:213], v[68:71]
	v_mfma_f32_16x16x32_bf16 v[64:67], v[226:229], v[210:213], v[64:67]
	s_setprio 0
	s_mov_b32 m0, s5
	s_add_u32 s98, s46, 0x80
	s_addc_u32 s99, s47, 0
	s_barrier
	ds_read_b128 v[170:173], v143 offset:16384
	ds_read_b128 v[174:177], v143 offset:17408
	ds_read_b128 v[178:181], v143 offset:18432
	ds_read_b128 v[182:185], v143 offset:19456
	ds_read_b128 v[186:189], v143 offset:20480
	ds_read_b128 v[190:193], v143 offset:21504
	ds_read_b128 v[206:209], v143 offset:22528
	ds_read_b128 v[210:213], v143 offset:23552
	global_load_lds_dwordx4 v128, s[46:47]
	s_mov_b32 m0, s50
	s_nop 0
	global_load_lds_dwordx4 v130, s[46:47]
	s_barrier
	s_waitcnt lgkmcnt(0)
	s_setprio 1
	v_mfma_f32_16x16x32_bf16 v[60:63], v[144:147], v[170:173], v[60:63]
	v_mfma_f32_16x16x32_bf16 v[56:59], v[162:165], v[170:173], v[56:59]
	v_mfma_f32_16x16x32_bf16 v[44:47], v[144:147], v[178:181], v[44:47]
	v_mfma_f32_16x16x32_bf16 v[40:43], v[162:165], v[178:181], v[40:43]
	v_mfma_f32_16x16x32_bf16 v[28:31], v[144:147], v[186:189], v[28:31]
	v_mfma_f32_16x16x32_bf16 v[24:27], v[162:165], v[186:189], v[24:27]
	v_mfma_f32_16x16x32_bf16 v[12:15], v[144:147], v[206:209], v[12:15]
	v_mfma_f32_16x16x32_bf16 v[8:11], v[162:165], v[206:209], v[8:11]
	v_mfma_f32_16x16x32_bf16 v[60:63], v[148:151], v[174:177], v[60:63]
	v_mfma_f32_16x16x32_bf16 v[56:59], v[166:169], v[174:177], v[56:59]
	v_mfma_f32_16x16x32_bf16 v[44:47], v[148:151], v[182:185], v[44:47]
	v_mfma_f32_16x16x32_bf16 v[40:43], v[166:169], v[182:185], v[40:43]
	v_mfma_f32_16x16x32_bf16 v[28:31], v[148:151], v[190:193], v[28:31]
	v_mfma_f32_16x16x32_bf16 v[24:27], v[166:169], v[190:193], v[24:27]
	v_mfma_f32_16x16x32_bf16 v[12:15], v[148:151], v[210:213], v[12:15]
	v_mfma_f32_16x16x32_bf16 v[8:11], v[166:169], v[210:213], v[8:11]
	s_setprio 0
	s_barrier
	s_add_u32 s62, s22, 0x80000
	s_addc_u32 s63, s23, 0
	s_add_i32 s61, s68, s4
	s_mov_b32 m0, s61
	s_nop 0
	global_load_lds_dwordx4 v152, s[62:63]
	s_add_i32 m0, s61, 0x2000
	s_nop 0
	global_load_lds_dwordx4 v132, s[62:63]
	s_waitcnt vmcnt(6)
	s_barrier
	s_setprio 1
	v_mfma_f32_16x16x32_bf16 v[52:55], v[214:217], v[170:173], v[52:55]
	v_mfma_f32_16x16x32_bf16 v[48:51], v[222:225], v[170:173], v[48:51]
	v_mfma_f32_16x16x32_bf16 v[36:39], v[214:217], v[178:181], v[36:39]
	v_mfma_f32_16x16x32_bf16 v[32:35], v[222:225], v[178:181], v[32:35]
	v_mfma_f32_16x16x32_bf16 v[20:23], v[214:217], v[186:189], v[20:23]
	v_mfma_f32_16x16x32_bf16 v[16:19], v[222:225], v[186:189], v[16:19]
	v_mfma_f32_16x16x32_bf16 v[4:7], v[214:217], v[206:209], v[4:7]
	v_mfma_f32_16x16x32_bf16 v[0:3], v[222:225], v[206:209], v[0:3]
	v_mfma_f32_16x16x32_bf16 v[52:55], v[218:221], v[174:177], v[52:55]
	v_mfma_f32_16x16x32_bf16 v[48:51], v[226:229], v[174:177], v[48:51]
	v_mfma_f32_16x16x32_bf16 v[36:39], v[218:221], v[182:185], v[36:39]
	v_mfma_f32_16x16x32_bf16 v[32:35], v[226:229], v[182:185], v[32:35]
	v_mfma_f32_16x16x32_bf16 v[20:23], v[218:221], v[190:193], v[20:23]
	v_mfma_f32_16x16x32_bf16 v[16:19], v[226:229], v[190:193], v[16:19]
	v_mfma_f32_16x16x32_bf16 v[4:7], v[218:221], v[210:213], v[4:7]
	v_mfma_f32_16x16x32_bf16 v[0:3], v[226:229], v[210:213], v[0:3]
	s_setprio 0
	s_add_i32 s61, 0, 0x18000
	s_barrier
	ds_read_b128 v[144:147], v232
	ds_read_b128 v[148:151], v232 offset:1024
	ds_read_b128 v[162:165], v232 offset:2048
	ds_read_b128 v[166:169], v232 offset:3072
	s_add_u32 s46, s46, 0x80000
	s_addc_u32 s47, s47, 0
	s_mov_b32 m0, s51
	ds_read_b128 v[170:173], v143 offset:32768
	ds_read_b128 v[174:177], v143 offset:33792
	ds_read_b128 v[178:181], v143 offset:34816
	ds_read_b128 v[182:185], v143 offset:35840
	ds_read_b128 v[186:189], v143 offset:36864
	ds_read_b128 v[190:193], v143 offset:37888
	ds_read_b128 v[206:209], v143 offset:38912
	ds_read_b128 v[210:213], v143 offset:39936
	global_load_lds_dwordx4 v128, s[46:47]
	s_mov_b32 m0, s52
	s_nop 0
	global_load_lds_dwordx4 v130, s[46:47]
	s_waitcnt lgkmcnt(8)
	s_barrier
	s_waitcnt lgkmcnt(0)
	s_setprio 1
	v_mfma_f32_16x16x32_bf16 v[124:127], v[144:147], v[170:173], v[124:127]
	v_mfma_f32_16x16x32_bf16 v[120:123], v[162:165], v[170:173], v[120:123]
	v_mfma_f32_16x16x32_bf16 v[108:111], v[144:147], v[178:181], v[108:111]
	v_mfma_f32_16x16x32_bf16 v[104:107], v[162:165], v[178:181], v[104:107]
	v_mfma_f32_16x16x32_bf16 v[92:95], v[144:147], v[186:189], v[92:95]
	v_mfma_f32_16x16x32_bf16 v[88:91], v[162:165], v[186:189], v[88:91]
	v_mfma_f32_16x16x32_bf16 v[76:79], v[144:147], v[206:209], v[76:79]
	v_mfma_f32_16x16x32_bf16 v[72:75], v[162:165], v[206:209], v[72:75]
	v_mfma_f32_16x16x32_bf16 v[124:127], v[148:151], v[174:177], v[124:127]
	v_mfma_f32_16x16x32_bf16 v[120:123], v[166:169], v[174:177], v[120:123]
	v_mfma_f32_16x16x32_bf16 v[108:111], v[148:151], v[182:185], v[108:111]
	v_mfma_f32_16x16x32_bf16 v[104:107], v[166:169], v[182:185], v[104:107]
	v_mfma_f32_16x16x32_bf16 v[92:95], v[148:151], v[190:193], v[92:95]
	v_mfma_f32_16x16x32_bf16 v[88:91], v[166:169], v[190:193], v[88:91]
	v_mfma_f32_16x16x32_bf16 v[76:79], v[148:151], v[210:213], v[76:79]
	v_mfma_f32_16x16x32_bf16 v[72:75], v[166:169], v[210:213], v[72:75]
	s_setprio 0
	s_barrier
	s_add_i32 s46, 0, 0x1c000
	s_add_i32 s47, s61, s4
	s_add_u32 s100, s22, 0x80
	s_addc_u32 s101, s23, 0
	s_mov_b32 m0, s47
	ds_read_b128 v[214:217], v233
	ds_read_b128 v[218:221], v233 offset:1024
	ds_read_b128 v[222:225], v233 offset:2048
	ds_read_b128 v[226:229], v233 offset:3072
	global_load_lds_dwordx4 v152, s[100:101]
	s_add_i32 m0, s47, 0x2000
	s_nop 0
	global_load_lds_dwordx4 v132, s[100:101]
	s_barrier
	s_waitcnt lgkmcnt(0)
	s_setprio 1
	v_mfma_f32_16x16x32_bf16 v[116:119], v[214:217], v[170:173], v[116:119]
	v_mfma_f32_16x16x32_bf16 v[112:115], v[222:225], v[170:173], v[112:115]
	v_mfma_f32_16x16x32_bf16 v[100:103], v[214:217], v[178:181], v[100:103]
	v_mfma_f32_16x16x32_bf16 v[96:99], v[222:225], v[178:181], v[96:99]
	v_mfma_f32_16x16x32_bf16 v[84:87], v[214:217], v[186:189], v[84:87]
	v_mfma_f32_16x16x32_bf16 v[80:83], v[222:225], v[186:189], v[80:83]
	v_mfma_f32_16x16x32_bf16 v[68:71], v[214:217], v[206:209], v[68:71]
	v_mfma_f32_16x16x32_bf16 v[64:67], v[222:225], v[206:209], v[64:67]
	v_mfma_f32_16x16x32_bf16 v[116:119], v[218:221], v[174:177], v[116:119]
	v_mfma_f32_16x16x32_bf16 v[112:115], v[226:229], v[174:177], v[112:115]
	v_mfma_f32_16x16x32_bf16 v[100:103], v[218:221], v[182:185], v[100:103]
	v_mfma_f32_16x16x32_bf16 v[96:99], v[226:229], v[182:185], v[96:99]
	v_mfma_f32_16x16x32_bf16 v[84:87], v[218:221], v[190:193], v[84:87]
	v_mfma_f32_16x16x32_bf16 v[80:83], v[226:229], v[190:193], v[80:83]
	v_mfma_f32_16x16x32_bf16 v[68:71], v[218:221], v[210:213], v[68:71]
	v_mfma_f32_16x16x32_bf16 v[64:67], v[226:229], v[210:213], v[64:67]
	s_setprio 0
	s_mov_b32 m0, s53
	s_barrier
	ds_read_b128 v[170:173], v143 offset:49152
	ds_read_b128 v[174:177], v143 offset:50176
	ds_read_b128 v[178:181], v143 offset:51200
	ds_read_b128 v[182:185], v143 offset:52224
	ds_read_b128 v[186:189], v143 offset:53248
	ds_read_b128 v[190:193], v143 offset:54272
	ds_read_b128 v[206:209], v143 offset:55296
	ds_read_b128 v[210:213], v143 offset:56320
	global_load_lds_dwordx4 v128, s[98:99]
	s_mov_b32 m0, s54
	s_nop 0
	global_load_lds_dwordx4 v130, s[98:99]
	s_barrier
	s_waitcnt lgkmcnt(0)
	s_setprio 1
	v_mfma_f32_16x16x32_bf16 v[60:63], v[144:147], v[170:173], v[60:63]
	v_mfma_f32_16x16x32_bf16 v[56:59], v[162:165], v[170:173], v[56:59]
	v_mfma_f32_16x16x32_bf16 v[44:47], v[144:147], v[178:181], v[44:47]
	v_mfma_f32_16x16x32_bf16 v[40:43], v[162:165], v[178:181], v[40:43]
	v_mfma_f32_16x16x32_bf16 v[28:31], v[144:147], v[186:189], v[28:31]
	v_mfma_f32_16x16x32_bf16 v[24:27], v[162:165], v[186:189], v[24:27]
	v_mfma_f32_16x16x32_bf16 v[12:15], v[144:147], v[206:209], v[12:15]
	v_mfma_f32_16x16x32_bf16 v[8:11], v[162:165], v[206:209], v[8:11]
	v_mfma_f32_16x16x32_bf16 v[60:63], v[148:151], v[174:177], v[60:63]
	v_mfma_f32_16x16x32_bf16 v[56:59], v[166:169], v[174:177], v[56:59]
	v_mfma_f32_16x16x32_bf16 v[44:47], v[148:151], v[182:185], v[44:47]
	v_mfma_f32_16x16x32_bf16 v[40:43], v[166:169], v[182:185], v[40:43]
	v_mfma_f32_16x16x32_bf16 v[28:31], v[148:151], v[190:193], v[28:31]
	v_mfma_f32_16x16x32_bf16 v[24:27], v[166:169], v[190:193], v[24:27]
	v_mfma_f32_16x16x32_bf16 v[12:15], v[148:151], v[210:213], v[12:15]
	v_mfma_f32_16x16x32_bf16 v[8:11], v[166:169], v[210:213], v[8:11]
	s_setprio 0
	s_barrier
	s_add_u32 s22, s22, 0x80080
	s_addc_u32 s23, s23, 0
	s_add_i32 s46, s46, s4
	s_mov_b32 m0, s46
	s_nop 0
	global_load_lds_dwordx4 v152, s[22:23]
	s_add_i32 m0, s46, 0x2000
	s_nop 0
	global_load_lds_dwordx4 v132, s[22:23]
	s_waitcnt vmcnt(6)
	s_barrier
	s_setprio 1
	v_mfma_f32_16x16x32_bf16 v[52:55], v[214:217], v[170:173], v[52:55]
	v_mfma_f32_16x16x32_bf16 v[48:51], v[222:225], v[170:173], v[48:51]
	v_mfma_f32_16x16x32_bf16 v[36:39], v[214:217], v[178:181], v[36:39]
	v_mfma_f32_16x16x32_bf16 v[32:35], v[222:225], v[178:181], v[32:35]
	v_mfma_f32_16x16x32_bf16 v[20:23], v[214:217], v[186:189], v[20:23]
	v_mfma_f32_16x16x32_bf16 v[16:19], v[222:225], v[186:189], v[16:19]
	v_mfma_f32_16x16x32_bf16 v[4:7], v[214:217], v[206:209], v[4:7]
	v_mfma_f32_16x16x32_bf16 v[0:3], v[222:225], v[206:209], v[0:3]
	v_mfma_f32_16x16x32_bf16 v[52:55], v[218:221], v[174:177], v[52:55]
	v_mfma_f32_16x16x32_bf16 v[48:51], v[226:229], v[174:177], v[48:51]
	v_mfma_f32_16x16x32_bf16 v[36:39], v[218:221], v[182:185], v[36:39]
	v_mfma_f32_16x16x32_bf16 v[32:35], v[226:229], v[182:185], v[32:35]
	v_mfma_f32_16x16x32_bf16 v[20:23], v[218:221], v[190:193], v[20:23]
	v_mfma_f32_16x16x32_bf16 v[16:19], v[226:229], v[190:193], v[16:19]
	v_mfma_f32_16x16x32_bf16 v[4:7], v[218:221], v[210:213], v[4:7]
	v_mfma_f32_16x16x32_bf16 v[0:3], v[226:229], v[210:213], v[0:3]
	s_setprio 0
	s_add_i32 s60, s60, 2
	s_add_u32 s20, s20, 0x100
	s_addc_u32 s21, s21, 0
	s_add_u32 s58, s58, 0x100
	s_addc_u32 s59, s59, 0
	s_cmp_gt_u32 s60, 29
	s_barrier
	s_cbranch_scc0 .LBB0_773
	v_lshl_add_u32 v144, s7, 8, v140
	v_max_f32_e32 v120, v120, v120
	v_ashrrev_i32_e32 v145, 31, v144
	v_max_f32_e32 v120, 0, v120
	v_max_f32_e32 v121, v121, v121
	v_max_f32_e32 v122, v122, v122
	v_lshl_or_b32 v138, s6, 8, v142
	v_lshlrev_b64 v[146:147], 14, v[144:145]
	v_mul_f32_e32 v145, v120, v120
	v_max_f32_e32 v120, v125, v125
	v_max_f32_e32 v121, 0, v121
	v_max_f32_e32 v122, 0, v122
	v_ashrrev_i32_e32 v139, 31, v138
	v_max_f32_e32 v124, v124, v124
	v_max_f32_e32 v120, 0, v120
	v_mul_f32_e32 v125, v121, v121
	v_max_f32_e32 v121, v126, v126
	v_mul_f32_e32 v126, v122, v122
	v_max_f32_e32 v122, v127, v127
	v_max_f32_e32 v123, v123, v123
	v_lshl_add_u64 v[146:147], s[16:17], 0, v[146:147]
	v_lshlrev_b64 v[148:149], 1, v[138:139]
	v_max_f32_e32 v124, 0, v124
	v_mul_f32_e32 v120, v120, v120
	v_max_f32_e32 v121, 0, v121
	v_max_f32_e32 v122, 0, v122
	v_max_f32_e32 v123, 0, v123
	v_max_f32_e32 v112, v112, v112
	v_lshl_add_u64 v[138:139], v[146:147], 0, v[148:149]
	v_mul_f32_e32 v124, v124, v124
	v_mul_f32_e32 v121, v121, v121
	v_mul_f32_e32 v122, v122, v122
	v_mul_f32_e32 v123, v123, v123
	v_cvt_pk_bf16_f32 v120, v124, v120
	v_max_f32_e32 v112, 0, v112
	v_max_f32_e32 v113, v113, v113
	v_max_f32_e32 v114, v114, v114
	v_cvt_pk_bf16_f32 v121, v121, v122
	v_cvt_pk_bf16_f32 v122, v145, v125
	v_cvt_pk_bf16_f32 v123, v126, v123
	global_store_dwordx4 v[138:139], v[120:123], off
	v_max_f32_e32 v113, 0, v113
	v_max_f32_e32 v114, 0, v114
	v_mul_f32_e32 v120, v112, v112
	v_max_f32_e32 v112, v117, v117
	v_max_f32_e32 v116, v116, v116
	v_max_f32_e32 v112, 0, v112
	v_mul_f32_e32 v117, v113, v113
	v_max_f32_e32 v113, v118, v118
	v_mul_f32_e32 v118, v114, v114
	v_max_f32_e32 v114, v119, v119
	v_max_f32_e32 v115, v115, v115
	v_max_f32_e32 v116, 0, v116
	v_mul_f32_e32 v112, v112, v112
	v_max_f32_e32 v113, 0, v113
	v_max_f32_e32 v114, 0, v114
	v_max_f32_e32 v115, 0, v115
	v_mul_f32_e32 v116, v116, v116
	v_mul_f32_e32 v113, v113, v113
	v_mul_f32_e32 v114, v114, v114
	v_mul_f32_e32 v115, v115, v115
	v_cvt_pk_bf16_f32 v112, v116, v112
	v_max_f32_e32 v104, v104, v104
	v_cvt_pk_bf16_f32 v113, v113, v114
	v_cvt_pk_bf16_f32 v114, v120, v117
	v_cvt_pk_bf16_f32 v115, v118, v115
	global_store_dwordx4 v[138:139], v[112:115], off offset:256
	v_max_f32_e32 v104, 0, v104
	v_max_f32_e32 v105, v105, v105
	v_or_b32_e32 v112, 16, v144
	v_max_f32_e32 v106, v106, v106
	v_ashrrev_i32_e32 v113, 31, v112
	v_mul_f32_e32 v114, v104, v104
	v_max_f32_e32 v104, v109, v109
	v_max_f32_e32 v105, 0, v105
	v_max_f32_e32 v106, 0, v106
	v_lshlrev_b64 v[112:113], 14, v[112:113]
	v_max_f32_e32 v108, v108, v108
	v_max_f32_e32 v104, 0, v104
	v_mul_f32_e32 v109, v105, v105
	v_max_f32_e32 v105, v110, v110
	v_mul_f32_e32 v110, v106, v106
	v_max_f32_e32 v106, v111, v111
	v_max_f32_e32 v107, v107, v107
	v_lshl_add_u64 v[112:113], s[16:17], 0, v[112:113]
	v_max_f32_e32 v108, 0, v108
	v_mul_f32_e32 v104, v104, v104
	v_max_f32_e32 v105, 0, v105
	v_max_f32_e32 v106, 0, v106
	v_max_f32_e32 v107, 0, v107
	v_max_f32_e32 v96, v96, v96
	v_lshl_add_u64 v[112:113], v[112:113], 0, v[148:149]
	v_mul_f32_e32 v108, v108, v108
	v_mul_f32_e32 v105, v105, v105
	v_mul_f32_e32 v106, v106, v106
	v_mul_f32_e32 v107, v107, v107
	v_cvt_pk_bf16_f32 v104, v108, v104
	v_max_f32_e32 v96, 0, v96
	v_max_f32_e32 v97, v97, v97
	v_max_f32_e32 v98, v98, v98
	v_cvt_pk_bf16_f32 v105, v105, v106
	v_cvt_pk_bf16_f32 v106, v114, v109
	v_cvt_pk_bf16_f32 v107, v110, v107
	global_store_dwordx4 v[112:113], v[104:107], off
	v_max_f32_e32 v97, 0, v97
	v_max_f32_e32 v98, 0, v98
	v_mul_f32_e32 v104, v96, v96
	v_max_f32_e32 v96, v101, v101
	v_max_f32_e32 v100, v100, v100
	v_max_f32_e32 v96, 0, v96
	v_mul_f32_e32 v101, v97, v97
	v_max_f32_e32 v97, v102, v102
	v_mul_f32_e32 v102, v98, v98
	v_max_f32_e32 v98, v103, v103
	v_max_f32_e32 v99, v99, v99
	v_max_f32_e32 v100, 0, v100
	v_mul_f32_e32 v96, v96, v96
	v_max_f32_e32 v97, 0, v97
	v_max_f32_e32 v98, 0, v98
	v_max_f32_e32 v99, 0, v99
	v_mul_f32_e32 v100, v100, v100
	v_mul_f32_e32 v97, v97, v97
	v_mul_f32_e32 v98, v98, v98
	v_mul_f32_e32 v99, v99, v99
	v_cvt_pk_bf16_f32 v96, v100, v96
	v_max_f32_e32 v88, v88, v88
	v_cvt_pk_bf16_f32 v97, v97, v98
	v_cvt_pk_bf16_f32 v98, v104, v101
	v_cvt_pk_bf16_f32 v99, v102, v99
	global_store_dwordx4 v[112:113], v[96:99], off offset:256
	v_max_f32_e32 v88, 0, v88
	v_max_f32_e32 v89, v89, v89
	v_or_b32_e32 v96, 32, v144
	v_max_f32_e32 v90, v90, v90
	v_ashrrev_i32_e32 v97, 31, v96
	v_mul_f32_e32 v98, v88, v88
	v_max_f32_e32 v88, v93, v93
	v_max_f32_e32 v89, 0, v89
	v_max_f32_e32 v90, 0, v90
	v_lshlrev_b64 v[96:97], 14, v[96:97]
	v_max_f32_e32 v92, v92, v92
	v_max_f32_e32 v88, 0, v88
	v_mul_f32_e32 v93, v89, v89
	v_max_f32_e32 v89, v94, v94
	v_mul_f32_e32 v94, v90, v90
	v_max_f32_e32 v90, v95, v95
	v_max_f32_e32 v91, v91, v91
	v_lshl_add_u64 v[96:97], s[16:17], 0, v[96:97]
	v_max_f32_e32 v92, 0, v92
	v_mul_f32_e32 v88, v88, v88
	v_max_f32_e32 v89, 0, v89
	v_max_f32_e32 v90, 0, v90
	v_max_f32_e32 v91, 0, v91
	v_max_f32_e32 v80, v80, v80
	v_lshl_add_u64 v[96:97], v[96:97], 0, v[148:149]
	v_mul_f32_e32 v92, v92, v92
	v_mul_f32_e32 v89, v89, v89
	v_mul_f32_e32 v90, v90, v90
	v_mul_f32_e32 v91, v91, v91
	v_cvt_pk_bf16_f32 v88, v92, v88
	v_max_f32_e32 v80, 0, v80
	v_max_f32_e32 v81, v81, v81
	v_max_f32_e32 v82, v82, v82
	v_cvt_pk_bf16_f32 v89, v89, v90
	v_cvt_pk_bf16_f32 v90, v98, v93
	v_cvt_pk_bf16_f32 v91, v94, v91
	global_store_dwordx4 v[96:97], v[88:91], off
	v_max_f32_e32 v81, 0, v81
	v_max_f32_e32 v82, 0, v82
	v_mul_f32_e32 v88, v80, v80
	v_max_f32_e32 v80, v85, v85
	v_max_f32_e32 v84, v84, v84
	v_max_f32_e32 v80, 0, v80
	v_mul_f32_e32 v85, v81, v81
	v_max_f32_e32 v81, v86, v86
	v_mul_f32_e32 v86, v82, v82
	v_max_f32_e32 v82, v87, v87
	v_max_f32_e32 v83, v83, v83
	v_max_f32_e32 v84, 0, v84
	v_mul_f32_e32 v80, v80, v80
	v_max_f32_e32 v81, 0, v81
	v_max_f32_e32 v82, 0, v82
	v_max_f32_e32 v83, 0, v83
	v_mul_f32_e32 v84, v84, v84
	v_mul_f32_e32 v81, v81, v81
	v_mul_f32_e32 v82, v82, v82
	v_mul_f32_e32 v83, v83, v83
	v_cvt_pk_bf16_f32 v80, v84, v80
	v_max_f32_e32 v72, v72, v72
	v_cvt_pk_bf16_f32 v81, v81, v82
	v_cvt_pk_bf16_f32 v82, v88, v85
	v_cvt_pk_bf16_f32 v83, v86, v83
	global_store_dwordx4 v[96:97], v[80:83], off offset:256
	v_max_f32_e32 v72, 0, v72
	v_max_f32_e32 v73, v73, v73
	v_or_b32_e32 v80, 48, v144
	v_max_f32_e32 v74, v74, v74
	v_ashrrev_i32_e32 v81, 31, v80
	v_mul_f32_e32 v82, v72, v72
	v_max_f32_e32 v72, v77, v77
	v_max_f32_e32 v73, 0, v73
	v_max_f32_e32 v74, 0, v74
	v_lshlrev_b64 v[80:81], 14, v[80:81]
	v_max_f32_e32 v76, v76, v76
	v_max_f32_e32 v72, 0, v72
	v_mul_f32_e32 v77, v73, v73
	v_max_f32_e32 v73, v78, v78
	v_mul_f32_e32 v78, v74, v74
	v_max_f32_e32 v74, v79, v79
	v_max_f32_e32 v75, v75, v75
	v_lshl_add_u64 v[80:81], s[16:17], 0, v[80:81]
	v_max_f32_e32 v76, 0, v76
	v_mul_f32_e32 v72, v72, v72
	v_max_f32_e32 v73, 0, v73
	v_max_f32_e32 v74, 0, v74
	v_max_f32_e32 v75, 0, v75
	v_max_f32_e32 v64, v64, v64
	v_max_f32_e32 v65, v65, v65
	v_max_f32_e32 v66, v66, v66
	v_lshl_add_u64 v[80:81], v[80:81], 0, v[148:149]
	v_mul_f32_e32 v76, v76, v76
	v_mul_f32_e32 v73, v73, v73
	v_mul_f32_e32 v74, v74, v74
	v_mul_f32_e32 v75, v75, v75
	v_cvt_pk_bf16_f32 v72, v76, v72
	v_max_f32_e32 v64, 0, v64
	v_max_f32_e32 v65, 0, v65
	v_max_f32_e32 v66, 0, v66
	v_cvt_pk_bf16_f32 v73, v73, v74
	v_cvt_pk_bf16_f32 v74, v82, v77
	v_cvt_pk_bf16_f32 v75, v78, v75
	global_store_dwordx4 v[80:81], v[72:75], off
	v_max_f32_e32 v68, v68, v68
	v_max_f32_e32 v67, v67, v67
	v_mul_f32_e32 v72, v64, v64
	v_max_f32_e32 v64, v69, v69
	v_mul_f32_e32 v69, v65, v65
	v_max_f32_e32 v65, v70, v70
	v_mul_f32_e32 v70, v66, v66
	v_max_f32_e32 v66, v71, v71
	v_max_f32_e32 v64, 0, v64
	v_max_f32_e32 v65, 0, v65
	v_max_f32_e32 v66, 0, v66
	v_max_f32_e32 v68, 0, v68
	v_mul_f32_e32 v64, v64, v64
	v_mul_f32_e32 v65, v65, v65
	v_max_f32_e32 v67, 0, v67
	v_mul_f32_e32 v66, v66, v66
	v_max_f32_e32 v56, v56, v56
	v_mul_f32_e32 v68, v68, v68
	v_mul_f32_e32 v67, v67, v67
	v_cvt_pk_bf16_f32 v64, v68, v64
	v_cvt_pk_bf16_f32 v65, v65, v66
	v_cvt_pk_bf16_f32 v66, v72, v69
	v_max_f32_e32 v56, 0, v56
	v_max_f32_e32 v57, v57, v57
	v_max_f32_e32 v58, v58, v58
	v_cvt_pk_bf16_f32 v67, v70, v67
	global_store_dwordx4 v[80:81], v[64:67], off offset:256
	v_max_f32_e32 v60, v60, v60
	v_max_f32_e32 v57, 0, v57
	v_mul_f32_e32 v66, v56, v56
	v_max_f32_e32 v56, v61, v61
	v_max_f32_e32 v58, 0, v58
	s_mov_b64 s[6:7], 0x200000
	v_max_f32_e32 v60, 0, v60
	v_max_f32_e32 v56, 0, v56
	v_mul_f32_e32 v61, v57, v57
	v_max_f32_e32 v57, v62, v62
	v_mul_f32_e32 v62, v58, v58
	v_max_f32_e32 v58, v63, v63
	v_lshl_add_u64 v[64:65], v[138:139], 0, s[6:7]
	v_mul_f32_e32 v60, v60, v60
	v_mul_f32_e32 v56, v56, v56
	v_max_f32_e32 v57, 0, v57
	v_max_f32_e32 v58, 0, v58
	v_max_f32_e32 v59, v59, v59
	s_mov_b32 s6, 0x200000
	v_mul_f32_e32 v57, v57, v57
	v_max_f32_e32 v59, 0, v59
	v_mul_f32_e32 v58, v58, v58
	v_cvt_pk_bf16_f32 v56, v60, v56
	v_add_co_u32_e32 v60, vcc, s6, v138
	v_max_f32_e32 v48, v48, v48
	v_max_f32_e32 v49, v49, v49
	v_max_f32_e32 v50, v50, v50
	v_mul_f32_e32 v59, v59, v59
	v_cvt_pk_bf16_f32 v57, v57, v58
	v_cvt_pk_bf16_f32 v58, v66, v61
	v_addc_co_u32_e32 v61, vcc, 0, v139, vcc
	v_max_f32_e32 v48, 0, v48
	v_max_f32_e32 v49, 0, v49
	v_max_f32_e32 v50, 0, v50
	v_cvt_pk_bf16_f32 v59, v62, v59
	global_store_dwordx4 v[60:61], v[56:59], off
	v_max_f32_e32 v52, v52, v52
	v_max_f32_e32 v51, v51, v51
	v_mul_f32_e32 v56, v48, v48
	v_max_f32_e32 v48, v53, v53
	v_mul_f32_e32 v53, v49, v49
	v_max_f32_e32 v49, v54, v54
	v_mul_f32_e32 v54, v50, v50
	v_max_f32_e32 v50, v55, v55
	v_max_f32_e32 v48, 0, v48
	v_max_f32_e32 v49, 0, v49
	v_max_f32_e32 v50, 0, v50
	v_max_f32_e32 v52, 0, v52
	v_mul_f32_e32 v48, v48, v48
	v_mul_f32_e32 v49, v49, v49
	v_max_f32_e32 v51, 0, v51
	v_mul_f32_e32 v50, v50, v50
	v_max_f32_e32 v40, v40, v40
	v_mul_f32_e32 v52, v52, v52
	v_mul_f32_e32 v51, v51, v51
	v_cvt_pk_bf16_f32 v48, v52, v48
	v_cvt_pk_bf16_f32 v49, v49, v50
	v_cvt_pk_bf16_f32 v50, v56, v53
	v_max_f32_e32 v40, 0, v40
	v_max_f32_e32 v41, v41, v41
	v_max_f32_e32 v42, v42, v42
	v_cvt_pk_bf16_f32 v51, v54, v51
	global_store_dwordx4 v[64:65], v[48:51], off offset:256
	v_max_f32_e32 v44, v44, v44
	v_max_f32_e32 v41, 0, v41
	v_mul_f32_e32 v50, v40, v40
	v_max_f32_e32 v40, v45, v45
	v_max_f32_e32 v42, 0, v42
	s_mov_b64 s[6:7], 0x240000
	v_max_f32_e32 v44, 0, v44
	v_max_f32_e32 v40, 0, v40
	v_mul_f32_e32 v45, v41, v41
	v_max_f32_e32 v41, v46, v46
	v_mul_f32_e32 v46, v42, v42
	v_max_f32_e32 v42, v47, v47
	v_lshl_add_u64 v[48:49], v[138:139], 0, s[6:7]
	v_mul_f32_e32 v44, v44, v44
	v_mul_f32_e32 v40, v40, v40
	v_max_f32_e32 v41, 0, v41
	v_max_f32_e32 v42, 0, v42
	v_max_f32_e32 v43, v43, v43
	s_mov_b32 s6, 0x240000
	v_mul_f32_e32 v41, v41, v41
	v_max_f32_e32 v43, 0, v43
	v_mul_f32_e32 v42, v42, v42
	v_cvt_pk_bf16_f32 v40, v44, v40
	v_add_co_u32_e32 v44, vcc, s6, v138
	v_max_f32_e32 v32, v32, v32
	v_max_f32_e32 v33, v33, v33
	v_max_f32_e32 v34, v34, v34
	v_mul_f32_e32 v43, v43, v43
	v_cvt_pk_bf16_f32 v41, v41, v42
	v_cvt_pk_bf16_f32 v42, v50, v45
	v_addc_co_u32_e32 v45, vcc, 0, v139, vcc
	v_max_f32_e32 v32, 0, v32
	v_max_f32_e32 v33, 0, v33
	v_max_f32_e32 v34, 0, v34
	v_cvt_pk_bf16_f32 v43, v46, v43
	global_store_dwordx4 v[44:45], v[40:43], off
	v_max_f32_e32 v36, v36, v36
	v_max_f32_e32 v35, v35, v35
	v_mul_f32_e32 v40, v32, v32
	v_max_f32_e32 v32, v37, v37
	v_mul_f32_e32 v37, v33, v33
	v_max_f32_e32 v33, v38, v38
	v_mul_f32_e32 v38, v34, v34
	v_max_f32_e32 v34, v39, v39
	v_max_f32_e32 v32, 0, v32
	v_max_f32_e32 v33, 0, v33
	v_max_f32_e32 v34, 0, v34
	v_max_f32_e32 v36, 0, v36
	v_mul_f32_e32 v32, v32, v32
	v_mul_f32_e32 v33, v33, v33
	v_max_f32_e32 v35, 0, v35
	v_mul_f32_e32 v34, v34, v34
	v_max_f32_e32 v24, v24, v24
	v_mul_f32_e32 v36, v36, v36
	v_mul_f32_e32 v35, v35, v35
	v_cvt_pk_bf16_f32 v32, v36, v32
	v_cvt_pk_bf16_f32 v33, v33, v34
	v_cvt_pk_bf16_f32 v34, v40, v37
	v_max_f32_e32 v24, 0, v24
	v_max_f32_e32 v25, v25, v25
	v_max_f32_e32 v26, v26, v26
	v_cvt_pk_bf16_f32 v35, v38, v35
	global_store_dwordx4 v[48:49], v[32:35], off offset:256
	v_max_f32_e32 v28, v28, v28
	v_max_f32_e32 v25, 0, v25
	v_mul_f32_e32 v34, v24, v24
	v_max_f32_e32 v24, v29, v29
	v_max_f32_e32 v26, 0, v26
	s_mov_b64 s[6:7], 0x280000
	v_max_f32_e32 v28, 0, v28
	v_max_f32_e32 v24, 0, v24
	v_mul_f32_e32 v29, v25, v25
	v_max_f32_e32 v25, v30, v30
	v_mul_f32_e32 v30, v26, v26
	v_max_f32_e32 v26, v31, v31
	v_lshl_add_u64 v[32:33], v[138:139], 0, s[6:7]
	v_mul_f32_e32 v28, v28, v28
	v_mul_f32_e32 v24, v24, v24
	v_max_f32_e32 v25, 0, v25
	v_max_f32_e32 v26, 0, v26
	v_max_f32_e32 v27, v27, v27
	s_mov_b32 s6, 0x280000
	v_mul_f32_e32 v25, v25, v25
	v_max_f32_e32 v27, 0, v27
	v_mul_f32_e32 v26, v26, v26
	v_cvt_pk_bf16_f32 v24, v28, v24
	v_add_co_u32_e32 v28, vcc, s6, v138
	v_max_f32_e32 v16, v16, v16
	v_max_f32_e32 v17, v17, v17
	v_max_f32_e32 v18, v18, v18
	v_mul_f32_e32 v27, v27, v27
	v_cvt_pk_bf16_f32 v25, v25, v26
	v_cvt_pk_bf16_f32 v26, v34, v29
	v_addc_co_u32_e32 v29, vcc, 0, v139, vcc
	v_max_f32_e32 v16, 0, v16
	v_max_f32_e32 v17, 0, v17
	v_max_f32_e32 v18, 0, v18
	v_cvt_pk_bf16_f32 v27, v30, v27
	global_store_dwordx4 v[28:29], v[24:27], off
	v_max_f32_e32 v20, v20, v20
	v_max_f32_e32 v19, v19, v19
	v_mul_f32_e32 v24, v16, v16
	v_max_f32_e32 v16, v21, v21
	v_mul_f32_e32 v21, v17, v17
	v_max_f32_e32 v17, v22, v22
	v_mul_f32_e32 v22, v18, v18
	v_max_f32_e32 v18, v23, v23
	v_max_f32_e32 v16, 0, v16
	v_max_f32_e32 v17, 0, v17
	v_max_f32_e32 v18, 0, v18
	v_max_f32_e32 v20, 0, v20
	v_mul_f32_e32 v16, v16, v16
	v_mul_f32_e32 v17, v17, v17
	v_max_f32_e32 v19, 0, v19
	v_mul_f32_e32 v18, v18, v18
	v_max_f32_e32 v8, v8, v8
	v_mul_f32_e32 v20, v20, v20
	v_mul_f32_e32 v19, v19, v19
	v_cvt_pk_bf16_f32 v16, v20, v16
	v_cvt_pk_bf16_f32 v17, v17, v18
	v_cvt_pk_bf16_f32 v18, v24, v21
	v_max_f32_e32 v8, 0, v8
	v_max_f32_e32 v9, v9, v9
	v_max_f32_e32 v10, v10, v10
	v_cvt_pk_bf16_f32 v19, v22, v19
	global_store_dwordx4 v[32:33], v[16:19], off offset:256
	v_max_f32_e32 v12, v12, v12
	v_max_f32_e32 v9, 0, v9
	v_mul_f32_e32 v18, v8, v8
	v_max_f32_e32 v8, v13, v13
	v_max_f32_e32 v10, 0, v10
	s_mov_b64 s[6:7], 0x2c0000
	v_max_f32_e32 v12, 0, v12
	v_max_f32_e32 v8, 0, v8
	v_mul_f32_e32 v13, v9, v9
	v_max_f32_e32 v9, v14, v14
	v_mul_f32_e32 v14, v10, v10
	v_max_f32_e32 v10, v15, v15
	v_lshl_add_u64 v[16:17], v[138:139], 0, s[6:7]
	v_mul_f32_e32 v12, v12, v12
	v_mul_f32_e32 v8, v8, v8
	v_max_f32_e32 v9, 0, v9
	v_max_f32_e32 v10, 0, v10
	v_max_f32_e32 v11, v11, v11
	s_mov_b32 s6, 0x2c0000
	v_mul_f32_e32 v9, v9, v9
	v_max_f32_e32 v11, 0, v11
	v_mul_f32_e32 v10, v10, v10
	v_cvt_pk_bf16_f32 v8, v12, v8
	v_add_co_u32_e32 v12, vcc, s6, v138
	v_max_f32_e32 v0, v0, v0
	v_max_f32_e32 v1, v1, v1
	v_max_f32_e32 v2, v2, v2
	v_mul_f32_e32 v11, v11, v11
	v_cvt_pk_bf16_f32 v9, v9, v10
	v_cvt_pk_bf16_f32 v10, v18, v13
	v_addc_co_u32_e32 v13, vcc, 0, v139, vcc
	v_max_f32_e32 v0, 0, v0
	v_max_f32_e32 v1, 0, v1
	v_max_f32_e32 v2, 0, v2
	v_cvt_pk_bf16_f32 v11, v14, v11
	global_store_dwordx4 v[12:13], v[8:11], off
	v_max_f32_e32 v3, v3, v3
	v_max_f32_e32 v4, v4, v4
	v_mul_f32_e32 v8, v0, v0
	v_max_f32_e32 v0, v5, v5
	v_mul_f32_e32 v5, v1, v1
	v_max_f32_e32 v1, v6, v6
	v_mul_f32_e32 v6, v2, v2
	v_max_f32_e32 v2, v7, v7
	v_max_f32_e32 v0, 0, v0
	v_max_f32_e32 v1, 0, v1
	v_max_f32_e32 v2, 0, v2
	v_max_f32_e32 v3, 0, v3
	v_max_f32_e32 v4, 0, v4
	v_mul_f32_e32 v0, v0, v0
	v_mul_f32_e32 v1, v1, v1
	v_mul_f32_e32 v2, v2, v2
	v_mul_f32_e32 v3, v3, v3
	s_and_b64 vcc, exec, s[38:39]
	s_mov_b32 s6, s24
	s_mov_b32 s7, s34
	s_mov_b64 s[22:23], s[44:45]
	s_mov_b64 s[20:21], s[42:43]
	v_mul_f32_e32 v4, v4, v4
	v_cvt_pk_bf16_f32 v0, v4, v0
	v_cvt_pk_bf16_f32 v1, v1, v2
	v_cvt_pk_bf16_f32 v2, v8, v5
	v_cvt_pk_bf16_f32 v3, v6, v3
	global_store_dwordx4 v[16:17], v[0:3], off offset:256
	s_cbranch_vccz .LBB0_770
	s_waitcnt vmcnt(0)
	v_readlane_b32 s34, v253, 45
	s_cmpk_gt_u32 s14, 0xff
	v_readlane_b32 s35, v253, 46
	s_cbranch_scc1 .LBB0_777
	s_barrier

.LBB0_836:
	s_add_u32 s22, s20, 0xffe00080
	s_addc_u32 s23, s21, -1
	s_add_i32 s78, 0, 0x10000
	ds_read_b128 v[120:123], v248
	ds_read_b128 v[124:127], v248 offset:1024
	ds_read_b128 v[132:135], v248 offset:2048
	ds_read_b128 v[136:139], v248 offset:3072
	s_cmpk_eq_i32 s69, 0x7c
	s_cselect_b32 s35, s6, s23
	s_cselect_b32 s34, s7, s22
	s_cselect_b32 s23, s1, s68
	s_cselect_b32 s22, s17, s63
	s_add_i32 m0, s52, 0xc000
	ds_read_b128 v[186:189], v185
	ds_read_b128 v[190:193], v185 offset:1024
	ds_read_b128 v[206:209], v185 offset:2048
	ds_read_b128 v[210:213], v185 offset:3072
	ds_read_b128 v[214:217], v185 offset:4096
	ds_read_b128 v[218:221], v185 offset:5120
	ds_read_b128 v[222:225], v185 offset:6144
	ds_read_b128 v[226:229], v185 offset:7168
	global_load_lds_dwordx4 v176, s[20:21]
	s_add_i32 m0, s52, 0xe000
	s_nop 0
	global_load_lds_dwordx4 v178, s[20:21]
	s_waitcnt lgkmcnt(8)
	s_barrier
	s_waitcnt lgkmcnt(0)
	s_setprio 1
	v_mfma_f32_16x16x32_bf16 v[140:143], v[120:123], v[186:189], v[140:143]
	v_mfma_f32_16x16x32_bf16 v[128:131], v[132:135], v[186:189], v[128:131]
	v_mfma_f32_16x16x32_bf16 v[112:115], v[120:123], v[206:209], v[112:115]
	v_mfma_f32_16x16x32_bf16 v[104:107], v[132:135], v[206:209], v[104:107]
	v_mfma_f32_16x16x32_bf16 v[96:99], v[120:123], v[214:217], v[96:99]
	v_mfma_f32_16x16x32_bf16 v[88:91], v[132:135], v[214:217], v[88:91]
	v_mfma_f32_16x16x32_bf16 v[80:83], v[120:123], v[222:225], v[80:83]
	v_mfma_f32_16x16x32_bf16 v[72:75], v[132:135], v[222:225], v[72:75]
	v_mfma_f32_16x16x32_bf16 v[140:143], v[124:127], v[190:193], v[140:143]
	v_mfma_f32_16x16x32_bf16 v[128:131], v[136:139], v[190:193], v[128:131]
	v_mfma_f32_16x16x32_bf16 v[112:115], v[124:127], v[210:213], v[112:115]
	v_mfma_f32_16x16x32_bf16 v[104:107], v[136:139], v[210:213], v[104:107]
	v_mfma_f32_16x16x32_bf16 v[96:99], v[124:127], v[218:221], v[96:99]
	v_mfma_f32_16x16x32_bf16 v[88:91], v[136:139], v[218:221], v[88:91]
	v_mfma_f32_16x16x32_bf16 v[80:83], v[124:127], v[226:229], v[80:83]
	v_mfma_f32_16x16x32_bf16 v[72:75], v[136:139], v[226:229], v[72:75]
	s_setprio 0
	s_barrier
	s_add_i32 s80, 0, 0x14000
	s_add_i32 s78, s78, s51
	ds_read_b128 v[230:233], v249
	ds_read_b128 v[234:237], v249 offset:1024
	ds_read_b128 v[238:241], v249 offset:2048
	ds_read_b128 v[242:245], v249 offset:3072
	s_mov_b32 m0, s78
	s_nop 0
	global_load_lds_dwordx4 v152, s[22:23]
	s_add_i32 m0, s78, 0x2000
	s_nop 0
	global_load_lds_dwordx4 v144, s[22:23]
	s_barrier
	s_waitcnt lgkmcnt(0)
	s_setprio 1
	v_mfma_f32_16x16x32_bf16 v[116:119], v[230:233], v[186:189], v[116:119]
	v_mfma_f32_16x16x32_bf16 v[108:111], v[238:241], v[186:189], v[108:111]
	v_mfma_f32_16x16x32_bf16 v[100:103], v[230:233], v[206:209], v[100:103]
	v_mfma_f32_16x16x32_bf16 v[92:95], v[238:241], v[206:209], v[92:95]
	v_mfma_f32_16x16x32_bf16 v[84:87], v[230:233], v[214:217], v[84:87]
	v_mfma_f32_16x16x32_bf16 v[76:79], v[238:241], v[214:217], v[76:79]
	v_mfma_f32_16x16x32_bf16 v[68:71], v[230:233], v[222:225], v[68:71]
	v_mfma_f32_16x16x32_bf16 v[64:67], v[238:241], v[222:225], v[64:67]
	v_mfma_f32_16x16x32_bf16 v[116:119], v[234:237], v[190:193], v[116:119]
	v_mfma_f32_16x16x32_bf16 v[108:111], v[242:245], v[190:193], v[108:111]
	v_mfma_f32_16x16x32_bf16 v[100:103], v[234:237], v[210:213], v[100:103]
	v_mfma_f32_16x16x32_bf16 v[92:95], v[242:245], v[210:213], v[92:95]
	v_mfma_f32_16x16x32_bf16 v[84:87], v[234:237], v[218:221], v[84:87]
	v_mfma_f32_16x16x32_bf16 v[76:79], v[242:245], v[218:221], v[76:79]
	v_mfma_f32_16x16x32_bf16 v[68:71], v[234:237], v[226:229], v[68:71]
	v_mfma_f32_16x16x32_bf16 v[64:67], v[242:245], v[226:229], v[64:67]
	s_setprio 0
	s_mov_b32 m0, s52
	s_add_u32 s98, s34, 0x80
	s_addc_u32 s99, s35, 0
	s_barrier
	ds_read_b128 v[186:189], v185 offset:16384
	ds_read_b128 v[190:193], v185 offset:17408
	ds_read_b128 v[206:209], v185 offset:18432
	ds_read_b128 v[210:213], v185 offset:19456
	ds_read_b128 v[214:217], v185 offset:20480
	ds_read_b128 v[218:221], v185 offset:21504
	ds_read_b128 v[222:225], v185 offset:22528
	ds_read_b128 v[226:229], v185 offset:23552
	global_load_lds_dwordx4 v148, s[34:35]
	s_mov_b32 m0, s53
	s_nop 0
	global_load_lds_dwordx4 v146, s[34:35]
	s_barrier
	s_waitcnt lgkmcnt(0)
	s_setprio 1
	v_mfma_f32_16x16x32_bf16 v[60:63], v[120:123], v[186:189], v[60:63]
	v_mfma_f32_16x16x32_bf16 v[56:59], v[132:135], v[186:189], v[56:59]
	v_mfma_f32_16x16x32_bf16 v[48:51], v[120:123], v[206:209], v[48:51]
	v_mfma_f32_16x16x32_bf16 v[40:43], v[132:135], v[206:209], v[40:43]
	v_mfma_f32_16x16x32_bf16 v[32:35], v[120:123], v[214:217], v[32:35]
	v_mfma_f32_16x16x32_bf16 v[24:27], v[132:135], v[214:217], v[24:27]
	v_mfma_f32_16x16x32_bf16 v[16:19], v[120:123], v[222:225], v[16:19]
	v_mfma_f32_16x16x32_bf16 v[8:11], v[132:135], v[222:225], v[8:11]
	v_mfma_f32_16x16x32_bf16 v[60:63], v[124:127], v[190:193], v[60:63]
	v_mfma_f32_16x16x32_bf16 v[56:59], v[136:139], v[190:193], v[56:59]
	v_mfma_f32_16x16x32_bf16 v[48:51], v[124:127], v[210:213], v[48:51]
	v_mfma_f32_16x16x32_bf16 v[40:43], v[136:139], v[210:213], v[40:43]
	v_mfma_f32_16x16x32_bf16 v[32:35], v[124:127], v[218:221], v[32:35]
	v_mfma_f32_16x16x32_bf16 v[24:27], v[136:139], v[218:221], v[24:27]
	v_mfma_f32_16x16x32_bf16 v[16:19], v[124:127], v[226:229], v[16:19]
	v_mfma_f32_16x16x32_bf16 v[8:11], v[136:139], v[226:229], v[8:11]
	s_setprio 0
	s_barrier
	s_add_u32 s78, s22, 0x200000
	s_addc_u32 s79, s23, 0
	s_add_i32 s80, s80, s51
	s_mov_b32 m0, s80
	s_nop 0
	global_load_lds_dwordx4 v152, s[78:79]
	s_add_i32 m0, s80, 0x2000
	s_nop 0
	global_load_lds_dwordx4 v144, s[78:79]
	s_waitcnt vmcnt(6)
	s_barrier
	s_setprio 1
	v_mfma_f32_16x16x32_bf16 v[52:55], v[230:233], v[186:189], v[52:55]
	v_mfma_f32_16x16x32_bf16 v[44:47], v[238:241], v[186:189], v[44:47]
	v_mfma_f32_16x16x32_bf16 v[36:39], v[230:233], v[206:209], v[36:39]
	v_mfma_f32_16x16x32_bf16 v[28:31], v[238:241], v[206:209], v[28:31]
	v_mfma_f32_16x16x32_bf16 v[20:23], v[230:233], v[214:217], v[20:23]
	v_mfma_f32_16x16x32_bf16 v[12:15], v[238:241], v[214:217], v[12:15]
	v_mfma_f32_16x16x32_bf16 v[4:7], v[230:233], v[222:225], v[4:7]
	v_mfma_f32_16x16x32_bf16 v[0:3], v[238:241], v[222:225], v[0:3]
	v_mfma_f32_16x16x32_bf16 v[52:55], v[234:237], v[190:193], v[52:55]
	v_mfma_f32_16x16x32_bf16 v[44:47], v[242:245], v[190:193], v[44:47]
	v_mfma_f32_16x16x32_bf16 v[36:39], v[234:237], v[210:213], v[36:39]
	v_mfma_f32_16x16x32_bf16 v[28:31], v[242:245], v[210:213], v[28:31]
	v_mfma_f32_16x16x32_bf16 v[20:23], v[234:237], v[218:221], v[20:23]
	v_mfma_f32_16x16x32_bf16 v[12:15], v[242:245], v[218:221], v[12:15]
	v_mfma_f32_16x16x32_bf16 v[4:7], v[234:237], v[226:229], v[4:7]
	v_mfma_f32_16x16x32_bf16 v[0:3], v[242:245], v[226:229], v[0:3]
	s_setprio 0
	s_add_i32 s78, 0, 0x18000
	s_barrier
	ds_read_b128 v[120:123], v250
	ds_read_b128 v[124:127], v250 offset:1024
	ds_read_b128 v[132:135], v250 offset:2048
	ds_read_b128 v[136:139], v250 offset:3072
	s_add_u32 s34, s34, 0x200000
	s_addc_u32 s35, s35, 0
	s_mov_b32 m0, s54
	ds_read_b128 v[186:189], v185 offset:32768
	ds_read_b128 v[190:193], v185 offset:33792
	ds_read_b128 v[206:209], v185 offset:34816
	ds_read_b128 v[210:213], v185 offset:35840
	ds_read_b128 v[214:217], v185 offset:36864
	ds_read_b128 v[218:221], v185 offset:37888
	ds_read_b128 v[222:225], v185 offset:38912
	ds_read_b128 v[226:229], v185 offset:39936
	global_load_lds_dwordx4 v148, s[34:35]
	s_mov_b32 m0, s55
	s_nop 0
	global_load_lds_dwordx4 v146, s[34:35]
	s_waitcnt lgkmcnt(8)
	s_barrier
	s_waitcnt lgkmcnt(0)
	s_setprio 1
	v_mfma_f32_16x16x32_bf16 v[140:143], v[120:123], v[186:189], v[140:143]
	v_mfma_f32_16x16x32_bf16 v[128:131], v[132:135], v[186:189], v[128:131]
	v_mfma_f32_16x16x32_bf16 v[112:115], v[120:123], v[206:209], v[112:115]
	v_mfma_f32_16x16x32_bf16 v[104:107], v[132:135], v[206:209], v[104:107]
	v_mfma_f32_16x16x32_bf16 v[96:99], v[120:123], v[214:217], v[96:99]
	v_mfma_f32_16x16x32_bf16 v[88:91], v[132:135], v[214:217], v[88:91]
	v_mfma_f32_16x16x32_bf16 v[80:83], v[120:123], v[222:225], v[80:83]
	v_mfma_f32_16x16x32_bf16 v[72:75], v[132:135], v[222:225], v[72:75]
	v_mfma_f32_16x16x32_bf16 v[140:143], v[124:127], v[190:193], v[140:143]
	v_mfma_f32_16x16x32_bf16 v[128:131], v[136:139], v[190:193], v[128:131]
	v_mfma_f32_16x16x32_bf16 v[112:115], v[124:127], v[210:213], v[112:115]
	v_mfma_f32_16x16x32_bf16 v[104:107], v[136:139], v[210:213], v[104:107]
	v_mfma_f32_16x16x32_bf16 v[96:99], v[124:127], v[218:221], v[96:99]
	v_mfma_f32_16x16x32_bf16 v[88:91], v[136:139], v[218:221], v[88:91]
	v_mfma_f32_16x16x32_bf16 v[80:83], v[124:127], v[226:229], v[80:83]
	v_mfma_f32_16x16x32_bf16 v[72:75], v[136:139], v[226:229], v[72:75]
	s_setprio 0
	s_barrier
	s_add_i32 s34, 0, 0x1c000
	s_add_i32 s35, s78, s51
	s_add_u32 s100, s22, 0x80
	s_addc_u32 s101, s23, 0
	s_mov_b32 m0, s35
	ds_read_b128 v[230:233], v251
	ds_read_b128 v[234:237], v251 offset:1024
	ds_read_b128 v[238:241], v251 offset:2048
	ds_read_b128 v[242:245], v251 offset:3072
	global_load_lds_dwordx4 v152, s[100:101]
	s_add_i32 m0, s35, 0x2000
	s_nop 0
	global_load_lds_dwordx4 v144, s[100:101]
	s_barrier
	s_waitcnt lgkmcnt(0)
	s_setprio 1
	v_mfma_f32_16x16x32_bf16 v[116:119], v[230:233], v[186:189], v[116:119]
	v_mfma_f32_16x16x32_bf16 v[108:111], v[238:241], v[186:189], v[108:111]
	v_mfma_f32_16x16x32_bf16 v[100:103], v[230:233], v[206:209], v[100:103]
	v_mfma_f32_16x16x32_bf16 v[92:95], v[238:241], v[206:209], v[92:95]
	v_mfma_f32_16x16x32_bf16 v[84:87], v[230:233], v[214:217], v[84:87]
	v_mfma_f32_16x16x32_bf16 v[76:79], v[238:241], v[214:217], v[76:79]
	v_mfma_f32_16x16x32_bf16 v[68:71], v[230:233], v[222:225], v[68:71]
	v_mfma_f32_16x16x32_bf16 v[64:67], v[238:241], v[222:225], v[64:67]
	v_mfma_f32_16x16x32_bf16 v[116:119], v[234:237], v[190:193], v[116:119]
	v_mfma_f32_16x16x32_bf16 v[108:111], v[242:245], v[190:193], v[108:111]
	v_mfma_f32_16x16x32_bf16 v[100:103], v[234:237], v[210:213], v[100:103]
	v_mfma_f32_16x16x32_bf16 v[92:95], v[242:245], v[210:213], v[92:95]
	v_mfma_f32_16x16x32_bf16 v[84:87], v[234:237], v[218:221], v[84:87]
	v_mfma_f32_16x16x32_bf16 v[76:79], v[242:245], v[218:221], v[76:79]
	v_mfma_f32_16x16x32_bf16 v[68:71], v[234:237], v[226:229], v[68:71]
	v_mfma_f32_16x16x32_bf16 v[64:67], v[242:245], v[226:229], v[64:67]
	s_setprio 0
	s_mov_b32 m0, s60
	s_barrier
	ds_read_b128 v[186:189], v185 offset:49152
	ds_read_b128 v[190:193], v185 offset:50176
	ds_read_b128 v[206:209], v185 offset:51200
	ds_read_b128 v[210:213], v185 offset:52224
	ds_read_b128 v[214:217], v185 offset:53248
	ds_read_b128 v[218:221], v185 offset:54272
	ds_read_b128 v[222:225], v185 offset:55296
	ds_read_b128 v[226:229], v185 offset:56320
	global_load_lds_dwordx4 v148, s[98:99]
	s_mov_b32 m0, s61
	s_nop 0
	global_load_lds_dwordx4 v146, s[98:99]
	s_barrier
	s_waitcnt lgkmcnt(0)
	s_setprio 1
	v_mfma_f32_16x16x32_bf16 v[60:63], v[120:123], v[186:189], v[60:63]
	v_mfma_f32_16x16x32_bf16 v[56:59], v[132:135], v[186:189], v[56:59]
	v_mfma_f32_16x16x32_bf16 v[48:51], v[120:123], v[206:209], v[48:51]
	v_mfma_f32_16x16x32_bf16 v[40:43], v[132:135], v[206:209], v[40:43]
	v_mfma_f32_16x16x32_bf16 v[32:35], v[120:123], v[214:217], v[32:35]
	v_mfma_f32_16x16x32_bf16 v[24:27], v[132:135], v[214:217], v[24:27]
	v_mfma_f32_16x16x32_bf16 v[16:19], v[120:123], v[222:225], v[16:19]
	v_mfma_f32_16x16x32_bf16 v[8:11], v[132:135], v[222:225], v[8:11]
	v_mfma_f32_16x16x32_bf16 v[60:63], v[124:127], v[190:193], v[60:63]
	v_mfma_f32_16x16x32_bf16 v[56:59], v[136:139], v[190:193], v[56:59]
	v_mfma_f32_16x16x32_bf16 v[48:51], v[124:127], v[210:213], v[48:51]
	v_mfma_f32_16x16x32_bf16 v[40:43], v[136:139], v[210:213], v[40:43]
	v_mfma_f32_16x16x32_bf16 v[32:35], v[124:127], v[218:221], v[32:35]
	v_mfma_f32_16x16x32_bf16 v[24:27], v[136:139], v[218:221], v[24:27]
	v_mfma_f32_16x16x32_bf16 v[16:19], v[124:127], v[226:229], v[16:19]
	v_mfma_f32_16x16x32_bf16 v[8:11], v[136:139], v[226:229], v[8:11]
	s_setprio 0
	s_barrier
	s_add_u32 s22, s22, 0x200080
	s_addc_u32 s23, s23, 0
	s_add_i32 s34, s34, s51
	s_mov_b32 m0, s34
	s_nop 0
	global_load_lds_dwordx4 v152, s[22:23]
	s_add_i32 m0, s34, 0x2000
	s_nop 0
	global_load_lds_dwordx4 v144, s[22:23]
	s_waitcnt vmcnt(6)
	s_barrier
	s_setprio 1
	v_mfma_f32_16x16x32_bf16 v[52:55], v[230:233], v[186:189], v[52:55]
	v_mfma_f32_16x16x32_bf16 v[44:47], v[238:241], v[186:189], v[44:47]
	v_mfma_f32_16x16x32_bf16 v[36:39], v[230:233], v[206:209], v[36:39]
	v_mfma_f32_16x16x32_bf16 v[28:31], v[238:241], v[206:209], v[28:31]
	v_mfma_f32_16x16x32_bf16 v[20:23], v[230:233], v[214:217], v[20:23]
	v_mfma_f32_16x16x32_bf16 v[12:15], v[238:241], v[214:217], v[12:15]
	v_mfma_f32_16x16x32_bf16 v[4:7], v[230:233], v[222:225], v[4:7]
	v_mfma_f32_16x16x32_bf16 v[0:3], v[238:241], v[222:225], v[0:3]
	v_mfma_f32_16x16x32_bf16 v[52:55], v[234:237], v[190:193], v[52:55]
	v_mfma_f32_16x16x32_bf16 v[44:47], v[242:245], v[190:193], v[44:47]
	v_mfma_f32_16x16x32_bf16 v[36:39], v[234:237], v[210:213], v[36:39]
	v_mfma_f32_16x16x32_bf16 v[28:31], v[242:245], v[210:213], v[28:31]
	v_mfma_f32_16x16x32_bf16 v[20:23], v[234:237], v[218:221], v[20:23]
	v_mfma_f32_16x16x32_bf16 v[12:15], v[242:245], v[218:221], v[12:15]
	v_mfma_f32_16x16x32_bf16 v[4:7], v[234:237], v[226:229], v[4:7]
	v_mfma_f32_16x16x32_bf16 v[0:3], v[242:245], v[226:229], v[0:3]
	s_setprio 0
	s_add_i32 s69, s69, 2
	s_add_u32 s20, s20, 0x100
	s_addc_u32 s21, s21, 0
	s_add_u32 s63, s63, 0x100
	s_addc_u32 s68, s68, 0
	s_cmpk_gt_u32 s69, 0x7d
	s_barrier
	s_cbranch_scc0 .LBB0_836
	v_readlane_b32 s98, v246, 0
	v_readlane_b32 s99, v246, 1
	s_cmp_eq_u32 s99, 0
	s_cbranch_scc1 .Lm2_epi
	s_and_b32 s100, s2, 0x7f
	s_lshl_b32 s100, s100, 18
	s_add_u32 s100, s100, 0x29800000
	s_add_u32 s100, s46, s100
	s_addc_u32 s101, s47, 0
	v_lshlrev_b32_e32 v186, 4, v182
	s_cmp_eq_u32 s99, 1
	s_cbranch_scc1 .Lm2_put_partial
	s_and_b32 s6, s2, 0x7f
	s_lshl_b32 s6, s6, 6
	s_add_u32 s6, s6, 0x2970a000
	s_add_u32 s6, s46, s6
	s_addc_u32 s7, s47, 0
	v_mov_b32_e32 v187, 0
	s_mov_b32 s99, 0
